# FoX steps: cross-half row-max merge moved off the serial chain between the MFMA groups into the rare rescale path (the branch only needs 'any lane above threshold')
# speedup vs baseline: 1.0064x; 1.0064x over previous
.LBB0_383:
	ds_read_b128 v[222:225], v184
	ds_read_b128 v[226:229], v184 offset:128
	ds_read_b128 v[230:233], v184 offset:32
	ds_read_b128 v[242:245], v184 offset:160
	ds_read_b128 v[246:249], v184 offset:64
	ds_read_b128 v[250:253], v184 offset:192
	v_add_u32_e32 v0, s56, v219
	ds_read_b64_tr_b16 v[176:177], v0 offset:24576
	ds_read_b64_tr_b16 v[178:179], v0 offset:25088
	v_add_f32_e32 v2, v64, v65
	v_add_f32_e32 v2, v66, v2
	v_add_f32_e32 v2, v67, v2
	v_add_f32_e32 v2, v68, v2
	v_add_f32_e32 v2, v69, v2
	v_cvt_pk_bf16_f32 v132, v64, v65
	v_cvt_pk_bf16_f32 v133, v66, v67
	s_waitcnt lgkmcnt(9)
	v_mfma_f32_32x32x16_bf16 v[80:95], v[172:175], v[140:143], 0
	ds_read_b64_tr_b16 v[172:173], v0 offset:28672
	ds_read_b64_tr_b16 v[174:175], v0 offset:29184
	v_add_f32_e32 v2, v70, v2
	v_add_f32_e32 v2, v71, v2
	v_add_f32_e32 v2, v72, v2
	v_add_f32_e32 v2, v73, v2
	v_cvt_pk_bf16_f32 v134, v68, v69
	v_cvt_pk_bf16_f32 v135, v70, v71
	s_waitcnt lgkmcnt(10)
	v_mfma_f32_32x32x16_bf16 v[96:111], v[168:171], v[140:143], 0
	ds_read_b64_tr_b16 v[168:169], v0 offset:25600
	ds_read_b64_tr_b16 v[170:171], v0 offset:26112
	v_add_f32_e32 v2, v74, v2
	v_add_f32_e32 v2, v75, v2
	v_add_f32_e32 v2, v76, v2
	v_add_f32_e32 v2, v77, v2
	v_cvt_pk_bf16_f32 v124, v72, v73
	v_cvt_pk_bf16_f32 v125, v74, v75
	s_waitcnt lgkmcnt(11)
	v_mfma_f32_32x32x16_bf16 v[80:95], v[164:167], v[136:139], v[80:95]
	ds_read_b64_tr_b16 v[164:165], v0 offset:29696
	ds_read_b64_tr_b16 v[166:167], v0 offset:30208
	v_add_f32_e32 v2, v78, v2
	v_add_f32_e32 v2, v79, v2
	v_add_f32_e32 v2, v48, v2
	v_add_f32_e32 v2, v49, v2
	v_cvt_pk_bf16_f32 v126, v76, v77
	v_cvt_pk_bf16_f32 v127, v78, v79
	s_waitcnt lgkmcnt(12)
	v_mfma_f32_32x32x16_bf16 v[96:111], v[160:163], v[136:139], v[96:111]
	ds_read_b64_tr_b16 v[160:161], v0 offset:26624
	ds_read_b64_tr_b16 v[162:163], v0 offset:27136
	v_add_f32_e32 v2, v50, v2
	v_add_f32_e32 v2, v51, v2
	v_add_f32_e32 v2, v52, v2
	v_add_f32_e32 v2, v53, v2
	v_cvt_pk_bf16_f32 v116, v48, v49
	v_cvt_pk_bf16_f32 v117, v50, v51
	s_waitcnt lgkmcnt(13)
	v_mfma_f32_32x32x16_bf16 v[80:95], v[156:159], v[128:131], v[80:95]
	ds_read_b64_tr_b16 v[10:11], v0 offset:30720
	ds_read_b64_tr_b16 v[12:13], v0 offset:31232
	v_add_f32_e32 v2, v54, v2
	v_add_f32_e32 v2, v55, v2
	v_add_f32_e32 v2, v56, v2
	v_add_f32_e32 v2, v57, v2
	v_cvt_pk_bf16_f32 v118, v52, v53
	v_cvt_pk_bf16_f32 v119, v54, v55
	s_waitcnt lgkmcnt(14)
	v_mfma_f32_32x32x16_bf16 v[96:111], v[148:151], v[128:131], v[96:111]
	ds_read_b64_tr_b16 v[6:7], v0 offset:27648
	ds_read_b64_tr_b16 v[8:9], v0 offset:28160
	v_add_f32_e32 v2, v58, v2
	v_add_f32_e32 v2, v59, v2
	v_add_f32_e32 v2, v60, v2
	v_add_f32_e32 v14, v61, v2
	v_cvt_pk_bf16_f32 v112, v56, v57
	v_cvt_pk_bf16_f32 v113, v58, v59
	s_waitcnt lgkmcnt(14)
	v_mfma_f32_32x32x16_bf16 v[80:95], v[152:155], v[120:123], v[80:95]
	ds_read_b64_tr_b16 v[2:3], v0 offset:31744
	ds_read_b64_tr_b16 v[4:5], v0 offset:32256
	v_add_f32_e32 v0, v62, v14
	v_add_f32_e32 v0, v63, v0
	v_add_f32_e32 v0, 0, v0
	v_cvt_pk_bf16_f32 v114, v60, v61
	v_cvt_pk_bf16_f32 v115, v62, v63
	v_mfma_f32_32x32x16_bf16 v[96:111], v[144:147], v[120:123], v[96:111]
	v_lshl_add_u64 v[14:15], v[182:183], 0, s[44:45]
	s_add_i32 s40, s43, s77
	s_mov_b32 s56, m0
	s_mov_b32 m0, s40
	s_nop 0
	global_load_lds_dwordx4 v[14:15], off
	s_mov_b32 m0, s56
	v_lshl_add_u64 v[14:15], v[180:181], 0, s[44:45]
	s_add_i32 s40, s41, s81
	s_mov_b32 s56, m0
	s_mov_b32 m0, s40
	s_nop 0
	global_load_lds_dwordx4 v[14:15], off
	s_mov_b32 m0, s56
	ds_read_b128 v[48:51], v184 offset:96
	ds_read_b128 v[52:55], v184 offset:224
	s_waitcnt lgkmcnt(2)
	v_pk_add_f32 v[80:81], v[80:81], v[222:223]
	v_pk_add_f32 v[82:83], v[82:83], v[224:225]
	v_pk_add_f32 v[96:97], v[96:97], v[226:227]
	v_pk_add_f32 v[98:99], v[98:99], v[228:229]
	v_pk_add_f32 v[84:85], v[84:85], v[230:231]
	v_pk_add_f32 v[86:87], v[86:87], v[232:233]
	v_pk_add_f32 v[100:101], v[100:101], v[242:243]
	v_pk_add_f32 v[102:103], v[102:103], v[244:245]
	v_pk_add_f32 v[88:89], v[88:89], v[246:247]
	v_pk_add_f32 v[90:91], v[90:91], v[248:249]
	v_pk_add_f32 v[104:105], v[104:105], v[250:251]
	v_pk_add_f32 v[106:107], v[106:107], v[252:253]
	s_waitcnt lgkmcnt(1)
	v_pk_add_f32 v[92:93], v[92:93], v[48:49]
	v_pk_add_f32 v[94:95], v[94:95], v[50:51]
	s_waitcnt lgkmcnt(0)
	v_pk_add_f32 v[108:109], v[108:109], v[52:53]
	v_pk_add_f32 v[110:111], v[110:111], v[54:55]
	s_nop 0
	s_nop 0
	v_pk_add_f32 v[48:49], v[80:81], v[196:197] op_sel_hi:[1,0] neg_lo:[0,1] neg_hi:[0,1]
	v_pk_add_f32 v[14:15], v[96:97], v[196:197] op_sel_hi:[1,0] neg_lo:[0,1] neg_hi:[0,1]
	v_pk_add_f32 v[66:67], v[82:83], v[196:197] op_sel_hi:[1,0] neg_lo:[0,1] neg_hi:[0,1]
	v_pk_add_f32 v[50:51], v[98:99], v[196:197] op_sel_hi:[1,0] neg_lo:[0,1] neg_hi:[0,1]
	v_max_f32_e32 v64, v48, v49
	v_pk_add_f32 v[68:69], v[84:85], v[196:197] op_sel_hi:[1,0] neg_lo:[0,1] neg_hi:[0,1]
	v_pk_add_f32 v[70:71], v[86:87], v[196:197] op_sel_hi:[1,0] neg_lo:[0,1] neg_hi:[0,1]
	v_max3_f32 v65, v66, v67, v15
	v_max3_f32 v64, v64, v14, v50
	v_pk_add_f32 v[52:53], v[100:101], v[196:197] op_sel_hi:[1,0] neg_lo:[0,1] neg_hi:[0,1]
	v_pk_add_f32 v[54:55], v[102:103], v[196:197] op_sel_hi:[1,0] neg_lo:[0,1] neg_hi:[0,1]
	v_max3_f32 v64, v64, v51, v68
	v_max3_f32 v65, v65, v70, v71
	v_pk_add_f32 v[72:73], v[88:89], v[196:197] op_sel_hi:[1,0] neg_lo:[0,1] neg_hi:[0,1]
	v_pk_add_f32 v[74:75], v[90:91], v[196:197] op_sel_hi:[1,0] neg_lo:[0,1] neg_hi:[0,1]
	v_max3_f32 v64, v64, v69, v52
	v_max3_f32 v65, v65, v54, v55
	v_pk_add_f32 v[56:57], v[104:105], v[196:197] op_sel_hi:[1,0] neg_lo:[0,1] neg_hi:[0,1]
	v_pk_add_f32 v[58:59], v[106:107], v[196:197] op_sel_hi:[1,0] neg_lo:[0,1] neg_hi:[0,1]
	v_max3_f32 v64, v64, v53, v72
	v_max3_f32 v65, v65, v74, v75
	v_pk_add_f32 v[76:77], v[92:93], v[196:197] op_sel_hi:[1,0] neg_lo:[0,1] neg_hi:[0,1]
	v_pk_add_f32 v[78:79], v[94:95], v[196:197] op_sel_hi:[1,0] neg_lo:[0,1] neg_hi:[0,1]
	v_max3_f32 v64, v64, v73, v56
	v_max3_f32 v65, v65, v58, v59
	v_pk_add_f32 v[60:61], v[108:109], v[196:197] op_sel_hi:[1,0] neg_lo:[0,1] neg_hi:[0,1]
	v_pk_add_f32 v[62:63], v[110:111], v[196:197] op_sel_hi:[1,0] neg_lo:[0,1] neg_hi:[0,1]
	v_max3_f32 v64, v64, v57, v76
	v_max3_f32 v65, v65, v78, v79
	v_max3_f32 v64, v64, v77, v60
	v_max3_f32 v65, v65, v62, v63
	v_max3_f32 v64, v64, v61, v65
	v_cmp_lt_f32_e32 vcc, s88, v64
	s_cmp_lg_u64 vcc, 0
	v_add_f32_e32 v0, v220, v0
	s_cselect_b64 s[56:57], -1, 0
	s_cbranch_vccnz .LBB0_391

.LBB0_386:
	ds_read_b128 v[222:225], v184 offset:256
	ds_read_b128 v[226:229], v184 offset:384
	ds_read_b128 v[230:233], v184 offset:288
	ds_read_b128 v[242:245], v184 offset:416
	ds_read_b128 v[246:249], v184 offset:320
	ds_read_b128 v[250:253], v184 offset:448
	s_add_i32 s40, s41, 0x2000
	s_cmpk_lg_i32 s41, 0x4000
	s_cselect_b32 s80, s40, 0
	v_add_u32_e32 v4, s43, v219
	ds_read_b64_tr_b16 v[160:161], v4 offset:24576
	ds_read_b64_tr_b16 v[162:163], v4 offset:25088
	v_add_f32_e32 v2, v64, v65
	v_add_f32_e32 v2, v66, v2
	v_add_f32_e32 v2, v67, v2
	v_add_f32_e32 v2, v68, v2
	v_add_f32_e32 v2, v69, v2
	v_cvt_pk_bf16_f32 v132, v64, v65
	v_cvt_pk_bf16_f32 v133, v66, v67
	s_waitcnt lgkmcnt(9)
	v_mfma_f32_32x32x16_bf16 v[80:95], v[80:83], v[140:143], 0
	ds_read_b64_tr_b16 v[156:157], v4 offset:28672
	ds_read_b64_tr_b16 v[158:159], v4 offset:29184
	v_add_f32_e32 v2, v70, v2
	v_add_f32_e32 v2, v71, v2
	v_add_f32_e32 v2, v72, v2
	v_add_f32_e32 v2, v73, v2
	v_cvt_pk_bf16_f32 v134, v68, v69
	v_cvt_pk_bf16_f32 v135, v70, v71
	s_waitcnt lgkmcnt(10)
	v_mfma_f32_32x32x16_bf16 v[96:111], v[96:99], v[140:143], 0
	ds_read_b64_tr_b16 v[152:153], v4 offset:25600
	ds_read_b64_tr_b16 v[154:155], v4 offset:26112
	v_add_f32_e32 v2, v74, v2
	v_add_f32_e32 v2, v75, v2
	v_add_f32_e32 v2, v76, v2
	v_add_f32_e32 v2, v77, v2
	v_cvt_pk_bf16_f32 v124, v72, v73
	v_cvt_pk_bf16_f32 v125, v74, v75
	s_waitcnt lgkmcnt(11)
	v_mfma_f32_32x32x16_bf16 v[80:95], v[148:151], v[136:139], v[80:95]
	ds_read_b64_tr_b16 v[148:149], v4 offset:29696
	ds_read_b64_tr_b16 v[150:151], v4 offset:30208
	v_add_f32_e32 v2, v78, v2
	v_add_f32_e32 v2, v79, v2
	v_add_f32_e32 v2, v48, v2
	v_add_f32_e32 v2, v49, v2
	v_cvt_pk_bf16_f32 v126, v76, v77
	v_cvt_pk_bf16_f32 v127, v78, v79
	s_waitcnt lgkmcnt(12)
	v_mfma_f32_32x32x16_bf16 v[96:111], v[144:147], v[136:139], v[96:111]
	ds_read_b64_tr_b16 v[144:145], v4 offset:26624
	ds_read_b64_tr_b16 v[146:147], v4 offset:27136
	v_add_f32_e32 v2, v50, v2
	v_add_f32_e32 v2, v51, v2
	v_add_f32_e32 v2, v52, v2
	v_add_f32_e32 v2, v53, v2
	v_cvt_pk_bf16_f32 v116, v48, v49
	v_cvt_pk_bf16_f32 v117, v50, v51
	s_waitcnt lgkmcnt(13)
	v_mfma_f32_32x32x16_bf16 v[80:95], v[176:179], v[128:131], v[80:95]
	ds_read_b64_tr_b16 v[10:11], v4 offset:30720
	ds_read_b64_tr_b16 v[12:13], v4 offset:31232
	v_add_f32_e32 v2, v54, v2
	v_add_f32_e32 v2, v55, v2
	v_add_f32_e32 v2, v56, v2
	v_add_f32_e32 v2, v57, v2
	v_cvt_pk_bf16_f32 v118, v52, v53
	v_cvt_pk_bf16_f32 v119, v54, v55
	s_waitcnt lgkmcnt(14)
	v_mfma_f32_32x32x16_bf16 v[96:111], v[168:171], v[128:131], v[96:111]
	ds_read_b64_tr_b16 v[6:7], v4 offset:27648
	ds_read_b64_tr_b16 v[8:9], v4 offset:28160
	v_add_f32_e32 v2, v58, v2
	v_add_f32_e32 v2, v59, v2
	v_add_f32_e32 v2, v60, v2
	v_add_f32_e32 v14, v61, v2
	v_cvt_pk_bf16_f32 v112, v56, v57
	v_cvt_pk_bf16_f32 v113, v58, v59
	s_waitcnt lgkmcnt(14)
	v_mfma_f32_32x32x16_bf16 v[80:95], v[172:175], v[120:123], v[80:95]
	ds_read_b64_tr_b16 v[2:3], v4 offset:31744
	ds_read_b64_tr_b16 v[4:5], v4 offset:32256
	v_add_f32_e32 v14, v62, v14
	v_add_f32_e32 v14, v63, v14
	v_add_f32_e32 v64, 0, v14
	v_cvt_pk_bf16_f32 v114, v60, v61
	v_cvt_pk_bf16_f32 v115, v62, v63
	v_mfma_f32_32x32x16_bf16 v[96:111], v[164:167], v[120:123], v[96:111]
	s_add_i32 s40, s41, s77
	s_mov_b32 s43, m0
	s_mov_b32 m0, s40
	s_nop 0
	global_load_lds_dwordx4 v[182:183], off
	s_mov_b32 m0, s43
	s_add_i32 s40, s80, s81
	s_mov_b32 s43, m0
	s_mov_b32 m0, s40
	s_nop 0
	global_load_lds_dwordx4 v[180:181], off
	s_mov_b32 m0, s43
	ds_read_b128 v[48:51], v184 offset:352
	ds_read_b128 v[52:55], v184 offset:480
	s_waitcnt lgkmcnt(2)
	v_pk_add_f32 v[80:81], v[80:81], v[222:223]
	v_pk_add_f32 v[82:83], v[82:83], v[224:225]
	v_pk_add_f32 v[96:97], v[96:97], v[226:227]
	v_pk_add_f32 v[98:99], v[98:99], v[228:229]
	v_pk_add_f32 v[84:85], v[84:85], v[230:231]
	v_pk_add_f32 v[86:87], v[86:87], v[232:233]
	v_pk_add_f32 v[100:101], v[100:101], v[242:243]
	v_pk_add_f32 v[102:103], v[102:103], v[244:245]
	v_pk_add_f32 v[88:89], v[88:89], v[246:247]
	v_pk_add_f32 v[90:91], v[90:91], v[248:249]
	v_pk_add_f32 v[104:105], v[104:105], v[250:251]
	v_pk_add_f32 v[106:107], v[106:107], v[252:253]
	s_waitcnt lgkmcnt(1)
	v_pk_add_f32 v[92:93], v[92:93], v[48:49]
	v_pk_add_f32 v[94:95], v[94:95], v[50:51]
	s_waitcnt lgkmcnt(0)
	v_pk_add_f32 v[108:109], v[108:109], v[52:53]
	v_pk_add_f32 v[110:111], v[110:111], v[54:55]
	s_nop 0
	s_nop 0
	v_pk_add_f32 v[48:49], v[80:81], v[196:197] op_sel_hi:[1,0] neg_lo:[0,1] neg_hi:[0,1]
	v_pk_add_f32 v[14:15], v[96:97], v[196:197] op_sel_hi:[1,0] neg_lo:[0,1] neg_hi:[0,1]
	v_pk_add_f32 v[66:67], v[82:83], v[196:197] op_sel_hi:[1,0] neg_lo:[0,1] neg_hi:[0,1]
	v_pk_add_f32 v[50:51], v[98:99], v[196:197] op_sel_hi:[1,0] neg_lo:[0,1] neg_hi:[0,1]
	v_max_f32_e32 v65, v48, v49
	v_pk_add_f32 v[68:69], v[84:85], v[196:197] op_sel_hi:[1,0] neg_lo:[0,1] neg_hi:[0,1]
	v_pk_add_f32 v[70:71], v[86:87], v[196:197] op_sel_hi:[1,0] neg_lo:[0,1] neg_hi:[0,1]
	v_max3_f32 v80, v66, v67, v15
	v_max3_f32 v65, v65, v14, v50
	v_pk_add_f32 v[52:53], v[100:101], v[196:197] op_sel_hi:[1,0] neg_lo:[0,1] neg_hi:[0,1]
	v_pk_add_f32 v[54:55], v[102:103], v[196:197] op_sel_hi:[1,0] neg_lo:[0,1] neg_hi:[0,1]
	v_max3_f32 v65, v65, v51, v68
	v_max3_f32 v80, v80, v70, v71
	v_pk_add_f32 v[72:73], v[88:89], v[196:197] op_sel_hi:[1,0] neg_lo:[0,1] neg_hi:[0,1]
	v_pk_add_f32 v[74:75], v[90:91], v[196:197] op_sel_hi:[1,0] neg_lo:[0,1] neg_hi:[0,1]
	v_max3_f32 v65, v65, v69, v52
	v_max3_f32 v80, v80, v54, v55
	v_pk_add_f32 v[56:57], v[104:105], v[196:197] op_sel_hi:[1,0] neg_lo:[0,1] neg_hi:[0,1]
	v_pk_add_f32 v[58:59], v[106:107], v[196:197] op_sel_hi:[1,0] neg_lo:[0,1] neg_hi:[0,1]
	v_max3_f32 v65, v65, v53, v72
	v_max3_f32 v80, v80, v74, v75
	v_pk_add_f32 v[76:77], v[92:93], v[196:197] op_sel_hi:[1,0] neg_lo:[0,1] neg_hi:[0,1]
	v_pk_add_f32 v[78:79], v[94:95], v[196:197] op_sel_hi:[1,0] neg_lo:[0,1] neg_hi:[0,1]
	v_max3_f32 v65, v65, v73, v56
	v_max3_f32 v80, v80, v58, v59
	v_pk_add_f32 v[60:61], v[108:109], v[196:197] op_sel_hi:[1,0] neg_lo:[0,1] neg_hi:[0,1]
	v_pk_add_f32 v[62:63], v[110:111], v[196:197] op_sel_hi:[1,0] neg_lo:[0,1] neg_hi:[0,1]
	v_max3_f32 v65, v65, v57, v76
	v_max3_f32 v80, v80, v78, v79
	v_max3_f32 v65, v65, v77, v60
	v_max3_f32 v80, v80, v62, v63
	v_add_f32_e32 v220, v0, v64
	v_max3_f32 v0, v65, v61, v80
	v_cmp_lt_f32_e32 vcc, s88, v0
	s_cmp_lg_u64 vcc, 0
	s_cselect_b64 s[56:57], -1, 0
	s_cbranch_vccnz .LBB0_394

.LBB0_391:
	v_mov_b32_e32 v65, v64
	s_nop 1
	v_permlane32_swap_b32_e32 v64, v65
	v_max_f32_e32 v65, v65, v65
	v_max_f32_e32 v64, v64, v64
	v_max_f32_e32 v64, v64, v65
	v_max_f32_e32 v64, v64, v64
	v_max_f32_e32 v65, 0, v64
	v_exp_f32_e64 v64, -v65
	s_and_saveexec_b64 s[60:61], s[4:5]
	ds_write_b32 v215, v64 offset:49152
	s_or_b64 exec, exec, s[60:61]
	v_sub_f32_e32 v48, v48, v65
	v_sub_f32_e32 v49, v49, v65
	v_sub_f32_e32 v66, v66, v65
	v_sub_f32_e32 v67, v67, v65
	v_sub_f32_e32 v68, v68, v65
	v_sub_f32_e32 v69, v69, v65
	v_sub_f32_e32 v70, v70, v65
	v_sub_f32_e32 v71, v71, v65
	v_sub_f32_e32 v72, v72, v65
	v_sub_f32_e32 v73, v73, v65
	v_sub_f32_e32 v74, v74, v65
	v_sub_f32_e32 v75, v75, v65
	v_sub_f32_e32 v76, v76, v65
	v_sub_f32_e32 v77, v77, v65
	v_sub_f32_e32 v78, v78, v65
	v_sub_f32_e32 v79, v79, v65
	v_sub_f32_e32 v14, v14, v65
	v_sub_f32_e32 v15, v15, v65
	v_sub_f32_e32 v50, v50, v65
	v_sub_f32_e32 v51, v51, v65
	v_sub_f32_e32 v52, v52, v65
	v_sub_f32_e32 v53, v53, v65
	v_sub_f32_e32 v54, v54, v65
	v_sub_f32_e32 v55, v55, v65
	v_sub_f32_e32 v56, v56, v65
	v_sub_f32_e32 v57, v57, v65
	v_sub_f32_e32 v58, v58, v65
	v_sub_f32_e32 v59, v59, v65
	v_sub_f32_e32 v60, v60, v65
	v_sub_f32_e32 v61, v61, v65
	v_sub_f32_e32 v62, v62, v65
	v_sub_f32_e32 v63, v63, v65
	v_add_f32_e32 v196, v196, v65
	v_mul_f32_e32 v0, v0, v64
	s_branch .LBB0_384
.LBB0_394:
	v_mov_b32_e32 v64, v0
	s_nop 1
	v_permlane32_swap_b32_e32 v0, v64
	v_max_f32_e32 v64, v64, v64
	v_max_f32_e32 v0, v0, v0
	v_max_f32_e32 v0, v0, v64
	v_max_f32_e32 v0, v0, v0
	v_max_f32_e32 v64, 0, v0
	v_exp_f32_e64 v0, -v64
	s_and_saveexec_b64 s[60:61], s[4:5]
	ds_write_b32 v215, v0 offset:49152
	s_or_b64 exec, exec, s[60:61]
	v_sub_f32_e32 v48, v48, v64
	v_sub_f32_e32 v49, v49, v64
	v_sub_f32_e32 v66, v66, v64
	v_sub_f32_e32 v67, v67, v64
	v_sub_f32_e32 v68, v68, v64
	v_sub_f32_e32 v69, v69, v64
	v_sub_f32_e32 v70, v70, v64
	v_sub_f32_e32 v71, v71, v64
	v_sub_f32_e32 v72, v72, v64
	v_sub_f32_e32 v73, v73, v64
	v_sub_f32_e32 v74, v74, v64
	v_sub_f32_e32 v75, v75, v64
	v_sub_f32_e32 v76, v76, v64
	v_sub_f32_e32 v77, v77, v64
	v_sub_f32_e32 v78, v78, v64
	v_sub_f32_e32 v79, v79, v64
	v_sub_f32_e32 v14, v14, v64
	v_sub_f32_e32 v15, v15, v64
	v_sub_f32_e32 v50, v50, v64
	v_sub_f32_e32 v51, v51, v64
	v_sub_f32_e32 v52, v52, v64
	v_sub_f32_e32 v53, v53, v64
	v_sub_f32_e32 v54, v54, v64
	v_sub_f32_e32 v55, v55, v64
	v_sub_f32_e32 v56, v56, v64
	v_sub_f32_e32 v57, v57, v64
	v_sub_f32_e32 v58, v58, v64
	v_sub_f32_e32 v59, v59, v64
	v_sub_f32_e32 v60, v60, v64
	v_sub_f32_e32 v61, v61, v64
	v_sub_f32_e32 v62, v62, v64
	v_sub_f32_e32 v63, v63, v64
	v_add_f32_e32 v196, v196, v64
	v_mul_f32_e32 v220, v220, v0
	s_branch .LBB0_387

.LBB0_399:
	v_add_u32_e32 v0, s40, v219
	ds_read_b64_tr_b16 v[176:177], v0 offset:24576
	ds_read_b64_tr_b16 v[178:179], v0 offset:25088
	v_add_f32_e32 v2, v64, v65
	v_add_f32_e32 v2, v66, v2
	v_add_f32_e32 v2, v67, v2
	v_add_f32_e32 v2, v68, v2
	v_add_f32_e32 v2, v69, v2
	v_cvt_pk_bf16_f32 v132, v64, v65
	v_cvt_pk_bf16_f32 v133, v66, v67
	s_waitcnt lgkmcnt(3)
	v_mfma_f32_32x32x16_bf16 v[80:95], v[172:175], v[140:143], 0
	ds_read_b64_tr_b16 v[172:173], v0 offset:28672
	ds_read_b64_tr_b16 v[174:175], v0 offset:29184
	v_add_f32_e32 v2, v70, v2
	v_add_f32_e32 v2, v71, v2
	v_add_f32_e32 v2, v72, v2
	v_add_f32_e32 v2, v73, v2
	v_cvt_pk_bf16_f32 v134, v68, v69
	v_cvt_pk_bf16_f32 v135, v70, v71
	s_waitcnt lgkmcnt(4)
	v_mfma_f32_32x32x16_bf16 v[96:111], v[168:171], v[140:143], 0
	ds_read_b64_tr_b16 v[168:169], v0 offset:25600
	ds_read_b64_tr_b16 v[170:171], v0 offset:26112
	v_add_f32_e32 v2, v74, v2
	v_add_f32_e32 v2, v75, v2
	v_add_f32_e32 v2, v76, v2
	v_add_f32_e32 v2, v77, v2
	v_cvt_pk_bf16_f32 v124, v72, v73
	v_cvt_pk_bf16_f32 v125, v74, v75
	v_mfma_f32_32x32x16_bf16 v[80:95], v[164:167], v[136:139], v[80:95]
	ds_read_b64_tr_b16 v[140:141], v0 offset:29696
	ds_read_b64_tr_b16 v[142:143], v0 offset:30208
	v_add_f32_e32 v2, v78, v2
	v_add_f32_e32 v2, v79, v2
	v_add_f32_e32 v2, v48, v2
	v_add_f32_e32 v2, v49, v2
	v_cvt_pk_bf16_f32 v126, v76, v77
	v_cvt_pk_bf16_f32 v127, v78, v79
	v_mfma_f32_32x32x16_bf16 v[96:111], v[160:163], v[136:139], v[96:111]
	ds_read_b64_tr_b16 v[136:137], v0 offset:26624
	ds_read_b64_tr_b16 v[138:139], v0 offset:27136
	v_add_f32_e32 v2, v50, v2
	v_add_f32_e32 v2, v51, v2
	v_add_f32_e32 v2, v52, v2
	v_add_f32_e32 v2, v53, v2
	v_cvt_pk_bf16_f32 v116, v48, v49
	v_cvt_pk_bf16_f32 v117, v50, v51
	v_mfma_f32_32x32x16_bf16 v[80:95], v[156:159], v[128:131], v[80:95]
	ds_read_b64_tr_b16 v[10:11], v0 offset:30720
	ds_read_b64_tr_b16 v[12:13], v0 offset:31232
	v_add_f32_e32 v2, v54, v2
	v_add_f32_e32 v2, v55, v2
	v_add_f32_e32 v2, v56, v2
	v_add_f32_e32 v2, v57, v2
	v_cvt_pk_bf16_f32 v118, v52, v53
	v_cvt_pk_bf16_f32 v119, v54, v55
	v_mfma_f32_32x32x16_bf16 v[96:111], v[148:151], v[128:131], v[96:111]
	ds_read_b64_tr_b16 v[6:7], v0 offset:27648
	ds_read_b64_tr_b16 v[8:9], v0 offset:28160
	v_add_f32_e32 v2, v58, v2
	v_add_f32_e32 v2, v59, v2
	v_add_f32_e32 v2, v60, v2
	v_add_f32_e32 v14, v61, v2
	v_cvt_pk_bf16_f32 v112, v56, v57
	v_cvt_pk_bf16_f32 v113, v58, v59
	v_mfma_f32_32x32x16_bf16 v[80:95], v[152:155], v[120:123], v[80:95]
	ds_read_b64_tr_b16 v[2:3], v0 offset:31744
	ds_read_b64_tr_b16 v[4:5], v0 offset:32256
	v_add_f32_e32 v0, v62, v14
	v_add_f32_e32 v0, v63, v0
	v_add_f32_e32 v0, 0, v0
	v_cvt_pk_bf16_f32 v114, v60, v61
	v_cvt_pk_bf16_f32 v115, v62, v63
	v_mfma_f32_32x32x16_bf16 v[96:111], v[144:147], v[120:123], v[96:111]
	s_lshl_b32 s4, s21, 8
	s_add_i32 s19, s19, s4
	v_lshl_add_u32 v14, v216, 2, s19
	v_add_u32_e32 v14, 0xffffff00, v14
	ds_read_b128 v[48:51], v14
	ds_read_b128 v[52:55], v14 offset:128
	s_waitcnt lgkmcnt(1)
	v_pk_add_f32 v[80:81], v[80:81], v[48:49]
	v_pk_add_f32 v[82:83], v[82:83], v[50:51]
	s_waitcnt lgkmcnt(0)
	s_nop 1
	v_pk_add_f32 v[96:97], v[96:97], v[52:53]
	v_pk_add_f32 v[98:99], v[98:99], v[54:55]
	s_nop 0
	ds_read_b128 v[48:51], v14 offset:32
	ds_read_b128 v[52:55], v14 offset:160
	s_waitcnt lgkmcnt(1)
	v_pk_add_f32 v[84:85], v[84:85], v[48:49]
	v_pk_add_f32 v[86:87], v[86:87], v[50:51]
	s_waitcnt lgkmcnt(0)
	v_pk_add_f32 v[100:101], v[100:101], v[52:53]
	v_pk_add_f32 v[102:103], v[102:103], v[54:55]
	s_nop 0
	ds_read_b128 v[48:51], v14 offset:64
	ds_read_b128 v[52:55], v14 offset:192
	s_waitcnt lgkmcnt(1)
	v_pk_add_f32 v[88:89], v[88:89], v[48:49]
	v_pk_add_f32 v[90:91], v[90:91], v[50:51]
	s_waitcnt lgkmcnt(0)
	v_pk_add_f32 v[104:105], v[104:105], v[52:53]
	v_pk_add_f32 v[106:107], v[106:107], v[54:55]
	s_nop 0
	ds_read_b128 v[48:51], v14 offset:96
	ds_read_b128 v[52:55], v14 offset:224
	s_waitcnt lgkmcnt(1)
	v_pk_add_f32 v[92:93], v[92:93], v[48:49]
	v_pk_add_f32 v[94:95], v[94:95], v[50:51]
	s_waitcnt lgkmcnt(0)
; __device__ __forceinline__ void cmask(f32x16&p0,f32x16&p1,int jb,int qrel,int hi){
;   const float NEG=-INFINITY; int kb=64*jb+4*hi;
;   #pragma unroll
;   for(int r=0;r<16;++r){int kv=kb+(r&3)+8*(r>>2); if(kv>qrel)p0[r]=NEG; if(kv+32>qrel)p1[r]=NEG;}
; }
	v_pk_add_f32 v[108:109], v[108:109], v[52:53]
	v_pk_add_f32 v[110:111], v[110:111], v[54:55]
	s_nop 0
	v_or_b32_e32 v14, 0xe0, v216
	v_or_b32_e32 v15, 0xc0, v216
	v_cmp_le_u32_e32 vcc, v14, v217
	v_or_b32_e32 v50, 0xc2, v216
	v_or_b32_e32 v51, 0xe2, v216
	v_cndmask_b32_e32 v14, v205, v96, vcc
	v_cmp_lt_u32_e32 vcc, v15, v217
	v_or_b32_e32 v53, 0xe3, v216
	v_or_b32_e32 v54, 0xc8, v216
	v_cndmask_b32_e32 v49, v205, v81, vcc
	v_cmp_le_u32_e32 vcc, v15, v217
	v_or_b32_e32 v15, 0xe1, v216
	v_or_b32_e32 v55, 0xe8, v216
	v_cndmask_b32_e32 v48, v205, v80, vcc
	v_cmp_le_u32_e32 vcc, v15, v217
	v_or_b32_e32 v57, 0xe9, v216
	v_or_b32_e32 v58, 0xca, v216
	v_cndmask_b32_e32 v15, v205, v97, vcc
	v_cmp_le_u32_e32 vcc, v50, v217
	v_or_b32_e32 v59, 0xea, v216
	v_or_b32_e32 v61, 0xeb, v216
	v_cndmask_b32_e32 v50, v205, v82, vcc
	v_cmp_le_u32_e32 vcc, v51, v217
	v_or_b32_e32 v51, 0xc3, v216
	v_or_b32_e32 v62, 0xd0, v216
	v_cndmask_b32_e32 v52, v205, v98, vcc
	v_cmp_le_u32_e32 vcc, v51, v217
	v_or_b32_e32 v63, 0xf0, v216
	v_or_b32_e32 v65, 0xf1, v216
	v_cndmask_b32_e32 v51, v205, v83, vcc
	v_cmp_le_u32_e32 vcc, v53, v217
	v_or_b32_e32 v66, 0xd2, v216
	v_pk_add_f32 v[48:49], v[48:49], v[196:197] op_sel_hi:[1,0] neg_lo:[0,1] neg_hi:[0,1]
	v_cndmask_b32_e32 v53, v205, v99, vcc
	v_cmp_le_u32_e32 vcc, v54, v217
	v_pk_add_f32 v[14:15], v[14:15], v[196:197] op_sel_hi:[1,0] neg_lo:[0,1] neg_hi:[0,1]
	v_add_f32_e32 v0, v220, v0
	v_cndmask_b32_e32 v54, v205, v84, vcc
	v_cmp_le_u32_e32 vcc, v55, v217
	v_or_b32_e32 v55, 0xc9, v216
	s_nop 0
	v_cndmask_b32_e32 v56, v205, v100, vcc
	v_cmp_le_u32_e32 vcc, v55, v217
	s_nop 1
	v_cndmask_b32_e32 v55, v205, v85, vcc
	v_cmp_le_u32_e32 vcc, v57, v217
	v_pk_add_f32 v[68:69], v[54:55], v[196:197] op_sel_hi:[1,0] neg_lo:[0,1] neg_hi:[0,1]
	s_nop 0
	v_cndmask_b32_e32 v57, v205, v101, vcc
	v_cmp_le_u32_e32 vcc, v58, v217
	s_nop 1
	v_cndmask_b32_e32 v58, v205, v86, vcc
	v_cmp_le_u32_e32 vcc, v59, v217
	v_or_b32_e32 v59, 0xcb, v216
	s_nop 0
	v_cndmask_b32_e32 v60, v205, v102, vcc
	v_cmp_le_u32_e32 vcc, v59, v217
	s_nop 1
	v_cndmask_b32_e32 v59, v205, v87, vcc
	v_cmp_le_u32_e32 vcc, v61, v217
	v_pk_add_f32 v[70:71], v[58:59], v[196:197] op_sel_hi:[1,0] neg_lo:[0,1] neg_hi:[0,1]
	s_nop 0
	v_cndmask_b32_e32 v61, v205, v103, vcc
	v_cmp_le_u32_e32 vcc, v62, v217
	v_pk_add_f32 v[54:55], v[60:61], v[196:197] op_sel_hi:[1,0] neg_lo:[0,1] neg_hi:[0,1]
	s_nop 0
	v_cndmask_b32_e32 v62, v205, v88, vcc
	v_cmp_le_u32_e32 vcc, v63, v217
	v_or_b32_e32 v63, 0xd1, v216
	s_nop 0
	v_cndmask_b32_e32 v64, v205, v104, vcc
	v_cmp_le_u32_e32 vcc, v63, v217
	s_nop 1
	v_cndmask_b32_e32 v63, v205, v89, vcc
	v_cmp_le_u32_e32 vcc, v65, v217
	v_pk_add_f32 v[72:73], v[62:63], v[196:197] op_sel_hi:[1,0] neg_lo:[0,1] neg_hi:[0,1]
	s_nop 0
	v_cndmask_b32_e32 v65, v205, v105, vcc
	v_cmp_le_u32_e32 vcc, v66, v217
	v_or_b32_e32 v66, 0xf2, v216
	s_nop 0
	v_cndmask_b32_e32 v74, v205, v90, vcc
	v_cmp_le_u32_e32 vcc, v66, v217
	v_or_b32_e32 v66, 0xd3, v216
	s_nop 0
	v_cndmask_b32_e32 v76, v205, v106, vcc
	v_cmp_le_u32_e32 vcc, v66, v217
	v_or_b32_e32 v66, 0xf3, v216
	s_nop 0
	v_cndmask_b32_e32 v75, v205, v91, vcc
	v_cmp_le_u32_e32 vcc, v66, v217
	v_or_b32_e32 v66, 0xd8, v216
	v_pk_add_f32 v[74:75], v[74:75], v[196:197] op_sel_hi:[1,0] neg_lo:[0,1] neg_hi:[0,1]
	v_cndmask_b32_e32 v77, v205, v107, vcc
	v_cmp_le_u32_e32 vcc, v66, v217
	v_or_b32_e32 v66, 0xf8, v216
	v_pk_add_f32 v[58:59], v[76:77], v[196:197] op_sel_hi:[1,0] neg_lo:[0,1] neg_hi:[0,1]
	v_cndmask_b32_e32 v78, v205, v92, vcc
	v_cmp_le_u32_e32 vcc, v66, v217
	v_or_b32_e32 v66, 0xd9, v216
	s_nop 0
	v_cndmask_b32_e32 v80, v205, v108, vcc
	v_cmp_le_u32_e32 vcc, v66, v217
	v_or_b32_e32 v66, 0xf9, v216
	s_nop 0
	v_cndmask_b32_e32 v79, v205, v93, vcc
	v_cmp_le_u32_e32 vcc, v66, v217
	v_or_b32_e32 v66, 0xda, v216
	v_pk_add_f32 v[76:77], v[78:79], v[196:197] op_sel_hi:[1,0] neg_lo:[0,1] neg_hi:[0,1]
	v_cndmask_b32_e32 v81, v205, v109, vcc
	v_cmp_le_u32_e32 vcc, v66, v217
	v_or_b32_e32 v66, 0xfa, v216
	v_pk_add_f32 v[60:61], v[80:81], v[196:197] op_sel_hi:[1,0] neg_lo:[0,1] neg_hi:[0,1]
	v_cndmask_b32_e32 v82, v205, v94, vcc
	v_cmp_le_u32_e32 vcc, v66, v217
	v_or_b32_e32 v66, 0xdb, v216
	s_nop 0
	v_cndmask_b32_e32 v84, v205, v110, vcc
	v_cmp_le_u32_e32 vcc, v66, v217
	v_or_b32_e32 v66, 0xfb, v216
	s_nop 0
	v_cndmask_b32_e32 v83, v205, v95, vcc
	v_cmp_le_u32_e32 vcc, v66, v217
	v_pk_add_f32 v[66:67], v[50:51], v[196:197] op_sel_hi:[1,0] neg_lo:[0,1] neg_hi:[0,1]
	v_pk_add_f32 v[50:51], v[52:53], v[196:197] op_sel_hi:[1,0] neg_lo:[0,1] neg_hi:[0,1]
	v_pk_add_f32 v[52:53], v[56:57], v[196:197] op_sel_hi:[1,0] neg_lo:[0,1] neg_hi:[0,1]
	v_pk_add_f32 v[56:57], v[64:65], v[196:197] op_sel_hi:[1,0] neg_lo:[0,1] neg_hi:[0,1]
	v_max_f32_e32 v64, v48, v49
	v_max3_f32 v65, v66, v67, v15
	v_max3_f32 v64, v64, v14, v50
	v_max3_f32 v64, v64, v51, v68
	v_max3_f32 v65, v65, v70, v71
	v_max3_f32 v64, v64, v69, v52
	v_max3_f32 v65, v65, v54, v55
	v_max3_f32 v64, v64, v53, v72
	v_max3_f32 v65, v65, v74, v75
	v_cndmask_b32_e32 v85, v205, v111, vcc
	v_pk_add_f32 v[78:79], v[82:83], v[196:197] op_sel_hi:[1,0] neg_lo:[0,1] neg_hi:[0,1]
	v_max3_f32 v64, v64, v73, v56
	v_max3_f32 v65, v65, v58, v59
	v_pk_add_f32 v[62:63], v[84:85], v[196:197] op_sel_hi:[1,0] neg_lo:[0,1] neg_hi:[0,1]
	v_max3_f32 v64, v64, v57, v76
	v_max3_f32 v65, v65, v78, v79
	v_max3_f32 v64, v64, v77, v60
	v_max3_f32 v65, v65, v62, v63
	v_max3_f32 v64, v64, v61, v65
	v_cmp_lt_f32_e32 vcc, s88, v64
	s_cmp_lg_u64 vcc, 0
	s_cselect_b64 s[4:5], -1, 0
	s_cbranch_vccnz .LBB0_454

.LBB0_410:
	v_pk_add_f32 v[48:49], v[80:81], v[196:197] op_sel_hi:[1,0] neg_lo:[0,1] neg_hi:[0,1]
	v_add_f32_e32 v220, v220, v14
	v_pk_add_f32 v[14:15], v[96:97], v[196:197] op_sel_hi:[1,0] neg_lo:[0,1] neg_hi:[0,1]
	v_pk_add_f32 v[66:67], v[82:83], v[196:197] op_sel_hi:[1,0] neg_lo:[0,1] neg_hi:[0,1]
	v_pk_add_f32 v[50:51], v[98:99], v[196:197] op_sel_hi:[1,0] neg_lo:[0,1] neg_hi:[0,1]
	v_max_f32_e32 v64, v48, v49
	v_pk_add_f32 v[68:69], v[84:85], v[196:197] op_sel_hi:[1,0] neg_lo:[0,1] neg_hi:[0,1]
	v_pk_add_f32 v[70:71], v[86:87], v[196:197] op_sel_hi:[1,0] neg_lo:[0,1] neg_hi:[0,1]
	v_max3_f32 v65, v66, v67, v15
	v_max3_f32 v64, v64, v14, v50
	v_pk_add_f32 v[52:53], v[100:101], v[196:197] op_sel_hi:[1,0] neg_lo:[0,1] neg_hi:[0,1]
	v_pk_add_f32 v[54:55], v[102:103], v[196:197] op_sel_hi:[1,0] neg_lo:[0,1] neg_hi:[0,1]
	v_max3_f32 v64, v64, v51, v68
	v_max3_f32 v65, v65, v70, v71
	v_pk_add_f32 v[72:73], v[88:89], v[196:197] op_sel_hi:[1,0] neg_lo:[0,1] neg_hi:[0,1]
	v_pk_add_f32 v[74:75], v[90:91], v[196:197] op_sel_hi:[1,0] neg_lo:[0,1] neg_hi:[0,1]
	v_max3_f32 v64, v64, v69, v52
	v_max3_f32 v65, v65, v54, v55
	v_pk_add_f32 v[56:57], v[104:105], v[196:197] op_sel_hi:[1,0] neg_lo:[0,1] neg_hi:[0,1]
	v_pk_add_f32 v[58:59], v[106:107], v[196:197] op_sel_hi:[1,0] neg_lo:[0,1] neg_hi:[0,1]
	v_max3_f32 v64, v64, v53, v72
	v_max3_f32 v65, v65, v74, v75
	v_pk_add_f32 v[76:77], v[92:93], v[196:197] op_sel_hi:[1,0] neg_lo:[0,1] neg_hi:[0,1]
	v_pk_add_f32 v[78:79], v[94:95], v[196:197] op_sel_hi:[1,0] neg_lo:[0,1] neg_hi:[0,1]
	v_max3_f32 v64, v64, v73, v56
	v_max3_f32 v65, v65, v58, v59
	v_pk_add_f32 v[60:61], v[108:109], v[196:197] op_sel_hi:[1,0] neg_lo:[0,1] neg_hi:[0,1]
	v_pk_add_f32 v[62:63], v[110:111], v[196:197] op_sel_hi:[1,0] neg_lo:[0,1] neg_hi:[0,1]
	v_max3_f32 v64, v64, v57, v76
	v_max3_f32 v65, v65, v78, v79
	v_max3_f32 v64, v64, v77, v60
	v_max3_f32 v65, v65, v62, v63
	v_max3_f32 v64, v64, v61, v65
	v_cmp_lt_f32_e32 vcc, s88, v64
	s_cmp_lg_u64 vcc, 0
	s_cselect_b64 s[60:61], -1, 0
	s_cbranch_vccnz .LBB0_448

.LBB0_421:
	v_pk_add_f32 v[48:49], v[80:81], v[196:197] op_sel_hi:[1,0] neg_lo:[0,1] neg_hi:[0,1]
	v_add_f32_e32 v220, v220, v14
	v_pk_add_f32 v[14:15], v[96:97], v[196:197] op_sel_hi:[1,0] neg_lo:[0,1] neg_hi:[0,1]
	v_pk_add_f32 v[66:67], v[82:83], v[196:197] op_sel_hi:[1,0] neg_lo:[0,1] neg_hi:[0,1]
	v_pk_add_f32 v[50:51], v[98:99], v[196:197] op_sel_hi:[1,0] neg_lo:[0,1] neg_hi:[0,1]
	v_max_f32_e32 v64, v48, v49
	v_pk_add_f32 v[68:69], v[84:85], v[196:197] op_sel_hi:[1,0] neg_lo:[0,1] neg_hi:[0,1]
	v_pk_add_f32 v[70:71], v[86:87], v[196:197] op_sel_hi:[1,0] neg_lo:[0,1] neg_hi:[0,1]
	v_max3_f32 v65, v66, v67, v15
	v_max3_f32 v64, v64, v14, v50
	v_pk_add_f32 v[52:53], v[100:101], v[196:197] op_sel_hi:[1,0] neg_lo:[0,1] neg_hi:[0,1]
	v_pk_add_f32 v[54:55], v[102:103], v[196:197] op_sel_hi:[1,0] neg_lo:[0,1] neg_hi:[0,1]
	v_max3_f32 v64, v64, v51, v68
	v_max3_f32 v65, v65, v70, v71
	v_pk_add_f32 v[72:73], v[88:89], v[196:197] op_sel_hi:[1,0] neg_lo:[0,1] neg_hi:[0,1]
	v_pk_add_f32 v[74:75], v[90:91], v[196:197] op_sel_hi:[1,0] neg_lo:[0,1] neg_hi:[0,1]
	v_max3_f32 v64, v64, v69, v52
	v_max3_f32 v65, v65, v54, v55
	v_pk_add_f32 v[56:57], v[104:105], v[196:197] op_sel_hi:[1,0] neg_lo:[0,1] neg_hi:[0,1]
	v_pk_add_f32 v[58:59], v[106:107], v[196:197] op_sel_hi:[1,0] neg_lo:[0,1] neg_hi:[0,1]
	v_max3_f32 v64, v64, v53, v72
	v_max3_f32 v65, v65, v74, v75
	v_pk_add_f32 v[76:77], v[92:93], v[196:197] op_sel_hi:[1,0] neg_lo:[0,1] neg_hi:[0,1]
	v_pk_add_f32 v[78:79], v[94:95], v[196:197] op_sel_hi:[1,0] neg_lo:[0,1] neg_hi:[0,1]
	v_max3_f32 v64, v64, v73, v56
	v_max3_f32 v65, v65, v58, v59
	v_pk_add_f32 v[60:61], v[108:109], v[196:197] op_sel_hi:[1,0] neg_lo:[0,1] neg_hi:[0,1]
	v_pk_add_f32 v[62:63], v[110:111], v[196:197] op_sel_hi:[1,0] neg_lo:[0,1] neg_hi:[0,1]
	v_max3_f32 v64, v64, v57, v76
	v_max3_f32 v65, v65, v78, v79
	v_max3_f32 v64, v64, v77, v60
	v_max3_f32 v65, v65, v62, v63
	v_max3_f32 v64, v64, v61, v65
	v_cmp_lt_f32_e32 vcc, s88, v64
	s_cmp_lg_u64 vcc, 0
	s_cselect_b64 s[64:65], -1, 0
	s_cbranch_vccnz .LBB0_451

.LBB0_448:
	v_mov_b32_e32 v65, v64
	s_nop 1
	v_permlane32_swap_b32_e32 v64, v65
	v_max_f32_e32 v65, v65, v65
	v_max_f32_e32 v64, v64, v64
	v_max_f32_e32 v64, v64, v65
	v_max_f32_e32 v64, v64, v64
	v_max_f32_e32 v65, 0, v64
	v_exp_f32_e64 v64, -v65
	s_and_saveexec_b64 s[62:63], s[4:5]
	ds_write_b32 v215, v64 offset:49152
	s_or_b64 exec, exec, s[62:63]
	v_sub_f32_e32 v48, v48, v65
	v_sub_f32_e32 v49, v49, v65
	v_sub_f32_e32 v66, v66, v65
	v_sub_f32_e32 v67, v67, v65
	v_sub_f32_e32 v68, v68, v65
	v_sub_f32_e32 v69, v69, v65
	v_sub_f32_e32 v70, v70, v65
	v_sub_f32_e32 v71, v71, v65
	v_sub_f32_e32 v72, v72, v65
	v_sub_f32_e32 v73, v73, v65
	v_sub_f32_e32 v74, v74, v65
	v_sub_f32_e32 v75, v75, v65
	v_sub_f32_e32 v76, v76, v65
	v_sub_f32_e32 v77, v77, v65
	v_sub_f32_e32 v78, v78, v65
	v_sub_f32_e32 v79, v79, v65
	v_sub_f32_e32 v14, v14, v65
	v_sub_f32_e32 v15, v15, v65
	v_sub_f32_e32 v50, v50, v65
	v_sub_f32_e32 v51, v51, v65
	v_sub_f32_e32 v52, v52, v65
	v_sub_f32_e32 v53, v53, v65
	v_sub_f32_e32 v54, v54, v65
	v_sub_f32_e32 v55, v55, v65
	v_sub_f32_e32 v56, v56, v65
	v_sub_f32_e32 v57, v57, v65
	v_sub_f32_e32 v58, v58, v65
	v_sub_f32_e32 v59, v59, v65
	v_sub_f32_e32 v60, v60, v65
	v_sub_f32_e32 v61, v61, v65
	v_sub_f32_e32 v62, v62, v65
	v_sub_f32_e32 v63, v63, v65
	v_add_f32_e32 v196, v196, v65
	v_mul_f32_e32 v220, v220, v64
	s_branch .LBB0_411
.LBB0_451:
	v_mov_b32_e32 v65, v64
	s_nop 1
	v_permlane32_swap_b32_e32 v64, v65
	v_max_f32_e32 v65, v65, v65
	v_max_f32_e32 v64, v64, v64
	v_max_f32_e32 v64, v64, v65
	v_max_f32_e32 v64, v64, v64
	v_max_f32_e32 v65, 0, v64
	v_exp_f32_e64 v64, -v65
	s_and_saveexec_b64 s[6:7], s[4:5]
	ds_write_b32 v215, v64 offset:49152
	s_or_b64 exec, exec, s[6:7]
	v_sub_f32_e32 v48, v48, v65
	v_sub_f32_e32 v49, v49, v65
	v_sub_f32_e32 v66, v66, v65
	v_sub_f32_e32 v67, v67, v65
	v_sub_f32_e32 v68, v68, v65
	v_sub_f32_e32 v69, v69, v65
	v_sub_f32_e32 v70, v70, v65
	v_sub_f32_e32 v71, v71, v65
	v_sub_f32_e32 v72, v72, v65
	v_sub_f32_e32 v73, v73, v65
	v_sub_f32_e32 v74, v74, v65
	v_sub_f32_e32 v75, v75, v65
	v_sub_f32_e32 v76, v76, v65
	v_sub_f32_e32 v77, v77, v65
	v_sub_f32_e32 v78, v78, v65
	v_sub_f32_e32 v79, v79, v65
	v_sub_f32_e32 v14, v14, v65
	v_sub_f32_e32 v15, v15, v65
	v_sub_f32_e32 v50, v50, v65
	v_sub_f32_e32 v51, v51, v65
	v_sub_f32_e32 v52, v52, v65
	v_sub_f32_e32 v53, v53, v65
	v_sub_f32_e32 v54, v54, v65
	v_sub_f32_e32 v55, v55, v65
	v_sub_f32_e32 v56, v56, v65
	v_sub_f32_e32 v57, v57, v65
	v_sub_f32_e32 v58, v58, v65
	v_sub_f32_e32 v59, v59, v65
	v_sub_f32_e32 v60, v60, v65
	v_sub_f32_e32 v61, v61, v65
	v_sub_f32_e32 v62, v62, v65
	v_sub_f32_e32 v63, v63, v65
	v_add_f32_e32 v196, v196, v65
	v_mul_f32_e32 v220, v220, v64
	s_branch .LBB0_422
.LBB0_454:
	v_mov_b32_e32 v65, v64
	s_nop 1
	v_permlane32_swap_b32_e32 v64, v65
	v_max_f32_e32 v65, v65, v65
	v_max_f32_e32 v64, v64, v64
	v_max_f32_e32 v64, v64, v65
	v_max_f32_e32 v64, v64, v64
	v_max_f32_e32 v65, 0, v64
	v_exp_f32_e64 v64, -v65
	v_cmp_gt_u32_e32 vcc, 32, v207
	s_and_saveexec_b64 s[6:7], vcc
	ds_write_b32 v215, v64 offset:49152
	s_or_b64 exec, exec, s[6:7]
	v_sub_f32_e32 v48, v48, v65
	v_sub_f32_e32 v49, v49, v65
	v_sub_f32_e32 v66, v66, v65
	v_sub_f32_e32 v67, v67, v65
	v_sub_f32_e32 v68, v68, v65
	v_sub_f32_e32 v69, v69, v65
	v_sub_f32_e32 v70, v70, v65
	v_sub_f32_e32 v71, v71, v65
	v_sub_f32_e32 v72, v72, v65
	v_sub_f32_e32 v73, v73, v65
	v_sub_f32_e32 v74, v74, v65
	v_sub_f32_e32 v75, v75, v65
	v_sub_f32_e32 v76, v76, v65
	v_sub_f32_e32 v77, v77, v65
	v_sub_f32_e32 v78, v78, v65
	v_sub_f32_e32 v79, v79, v65
	v_sub_f32_e32 v14, v14, v65
	v_sub_f32_e32 v15, v15, v65
	v_sub_f32_e32 v50, v50, v65
	v_sub_f32_e32 v51, v51, v65
	v_sub_f32_e32 v52, v52, v65
	v_sub_f32_e32 v53, v53, v65
	v_sub_f32_e32 v54, v54, v65
	v_sub_f32_e32 v55, v55, v65
	v_sub_f32_e32 v56, v56, v65
	v_sub_f32_e32 v57, v57, v65
	v_sub_f32_e32 v58, v58, v65
	v_sub_f32_e32 v59, v59, v65
	v_sub_f32_e32 v60, v60, v65
	v_sub_f32_e32 v61, v61, v65
	v_sub_f32_e32 v62, v62, v65
	v_sub_f32_e32 v63, v63, v65
	v_mul_f32_e32 v0, v0, v64
	s_branch .LBB0_400

; __device__ __forceinline__ void biasf(f32x16&p0,f32x16&p1,const __attribute__((address_space(3))) float*p){
;   #pragma unroll
;   for(int j=0;j<4;++j){ const f32x4a a=*(const __attribute__((address_space(3))) f32x4a*)(p+8*j), b=*(const __attribute__((address_space(3))) f32x4a*)(p+32+8*j);
;     p0[4*j]+=a[0];p0[4*j+1]+=a[1];p0[4*j+2]+=a[2];p0[4*j+3]+=a[3]; p1[4*j]+=b[0];p1[4*j+1]+=b[1];p1[4*j+2]+=b[2];p1[4*j+3]+=b[3];
;     asm volatile("":"+v"(p0),"+v"(p1)); __builtin_amdgcn_sched_barrier(0); }
.LBB0_1423:
	ds_read_b128 v[222:225], v184
	ds_read_b128 v[226:229], v184 offset:128
	ds_read_b128 v[230:233], v184 offset:32
	ds_read_b128 v[242:245], v184 offset:160
	ds_read_b128 v[246:249], v184 offset:64
	ds_read_b128 v[250:253], v184 offset:192
	v_add_u32_e32 v0, s54, v219
	ds_read_b64_tr_b16 v[176:177], v0 offset:24576
	ds_read_b64_tr_b16 v[178:179], v0 offset:25088
	v_add_f32_e32 v2, v64, v65
	v_add_f32_e32 v2, v66, v2
	v_add_f32_e32 v2, v67, v2
	v_add_f32_e32 v2, v68, v2
	v_add_f32_e32 v2, v69, v2
	v_cvt_pk_bf16_f32 v132, v64, v65
	v_cvt_pk_bf16_f32 v133, v66, v67
	s_waitcnt lgkmcnt(9)
	v_mfma_f32_32x32x16_bf16 v[80:95], v[172:175], v[140:143], 0
	ds_read_b64_tr_b16 v[172:173], v0 offset:28672
	ds_read_b64_tr_b16 v[174:175], v0 offset:29184
	v_add_f32_e32 v2, v70, v2
	v_add_f32_e32 v2, v71, v2
	v_add_f32_e32 v2, v72, v2
	v_add_f32_e32 v2, v73, v2
	v_cvt_pk_bf16_f32 v134, v68, v69
	v_cvt_pk_bf16_f32 v135, v70, v71
	s_waitcnt lgkmcnt(10)
	v_mfma_f32_32x32x16_bf16 v[96:111], v[168:171], v[140:143], 0
	ds_read_b64_tr_b16 v[168:169], v0 offset:25600
	ds_read_b64_tr_b16 v[170:171], v0 offset:26112
	v_add_f32_e32 v2, v74, v2
	v_add_f32_e32 v2, v75, v2
	v_add_f32_e32 v2, v76, v2
	v_add_f32_e32 v2, v77, v2
	v_cvt_pk_bf16_f32 v124, v72, v73
	v_cvt_pk_bf16_f32 v125, v74, v75
	s_waitcnt lgkmcnt(11)
	v_mfma_f32_32x32x16_bf16 v[80:95], v[164:167], v[136:139], v[80:95]
	ds_read_b64_tr_b16 v[164:165], v0 offset:29696
	ds_read_b64_tr_b16 v[166:167], v0 offset:30208
	v_add_f32_e32 v2, v78, v2
	v_add_f32_e32 v2, v79, v2
	v_add_f32_e32 v2, v48, v2
	v_add_f32_e32 v2, v49, v2
	v_cvt_pk_bf16_f32 v126, v76, v77
	v_cvt_pk_bf16_f32 v127, v78, v79
	s_waitcnt lgkmcnt(12)
	v_mfma_f32_32x32x16_bf16 v[96:111], v[160:163], v[136:139], v[96:111]
	ds_read_b64_tr_b16 v[160:161], v0 offset:26624
	ds_read_b64_tr_b16 v[162:163], v0 offset:27136
	v_add_f32_e32 v2, v50, v2
	v_add_f32_e32 v2, v51, v2
	v_add_f32_e32 v2, v52, v2
	v_add_f32_e32 v2, v53, v2
	v_cvt_pk_bf16_f32 v116, v48, v49
	v_cvt_pk_bf16_f32 v117, v50, v51
	s_waitcnt lgkmcnt(13)
	v_mfma_f32_32x32x16_bf16 v[80:95], v[156:159], v[128:131], v[80:95]
	ds_read_b64_tr_b16 v[10:11], v0 offset:30720
	ds_read_b64_tr_b16 v[12:13], v0 offset:31232
	v_add_f32_e32 v2, v54, v2
	v_add_f32_e32 v2, v55, v2
	v_add_f32_e32 v2, v56, v2
	v_add_f32_e32 v2, v57, v2
	v_cvt_pk_bf16_f32 v118, v52, v53
	v_cvt_pk_bf16_f32 v119, v54, v55
	s_waitcnt lgkmcnt(14)
	v_mfma_f32_32x32x16_bf16 v[96:111], v[148:151], v[128:131], v[96:111]
	ds_read_b64_tr_b16 v[6:7], v0 offset:27648
	ds_read_b64_tr_b16 v[8:9], v0 offset:28160
	v_add_f32_e32 v2, v58, v2
	v_add_f32_e32 v2, v59, v2
	v_add_f32_e32 v2, v60, v2
	v_add_f32_e32 v14, v61, v2
	v_cvt_pk_bf16_f32 v112, v56, v57
	v_cvt_pk_bf16_f32 v113, v58, v59
	s_waitcnt lgkmcnt(14)
	v_mfma_f32_32x32x16_bf16 v[80:95], v[152:155], v[120:123], v[80:95]
	ds_read_b64_tr_b16 v[2:3], v0 offset:31744
	ds_read_b64_tr_b16 v[4:5], v0 offset:32256
	v_add_f32_e32 v0, v62, v14
	v_add_f32_e32 v0, v63, v0
	v_add_f32_e32 v0, 0, v0
	v_cvt_pk_bf16_f32 v114, v60, v61
	v_cvt_pk_bf16_f32 v115, v62, v63
	v_mfma_f32_32x32x16_bf16 v[96:111], v[144:147], v[120:123], v[96:111]
	v_lshl_add_u64 v[14:15], v[182:183], 0, s[42:43]
	s_add_i32 s54, s97, s66
	s_mov_b32 s55, m0
	s_mov_b32 m0, s54
	s_nop 0
	global_load_lds_dwordx4 v[14:15], off
	s_mov_b32 m0, s55
	v_lshl_add_u64 v[14:15], v[180:181], 0, s[42:43]
	s_add_i32 s54, s62, s67
	s_mov_b32 s55, m0
	s_mov_b32 m0, s54
	s_nop 0
	global_load_lds_dwordx4 v[14:15], off
	s_mov_b32 m0, s55
	ds_read_b128 v[48:51], v184 offset:96
	ds_read_b128 v[52:55], v184 offset:224
	s_waitcnt lgkmcnt(2)
	v_pk_add_f32 v[80:81], v[80:81], v[222:223]
	v_pk_add_f32 v[82:83], v[82:83], v[224:225]
	v_pk_add_f32 v[96:97], v[96:97], v[226:227]
	v_pk_add_f32 v[98:99], v[98:99], v[228:229]
	v_pk_add_f32 v[84:85], v[84:85], v[230:231]
	v_pk_add_f32 v[86:87], v[86:87], v[232:233]
	v_pk_add_f32 v[100:101], v[100:101], v[242:243]
	v_pk_add_f32 v[102:103], v[102:103], v[244:245]
	v_pk_add_f32 v[88:89], v[88:89], v[246:247]
	v_pk_add_f32 v[90:91], v[90:91], v[248:249]
	v_pk_add_f32 v[104:105], v[104:105], v[250:251]
	v_pk_add_f32 v[106:107], v[106:107], v[252:253]
	s_waitcnt lgkmcnt(1)
	v_pk_add_f32 v[92:93], v[92:93], v[48:49]
	v_pk_add_f32 v[94:95], v[94:95], v[50:51]
	s_waitcnt lgkmcnt(0)
	v_pk_add_f32 v[108:109], v[108:109], v[52:53]
	v_pk_add_f32 v[110:111], v[110:111], v[54:55]
	s_nop 0
	s_nop 0
	v_pk_add_f32 v[48:49], v[80:81], v[196:197] op_sel_hi:[1,0] neg_lo:[0,1] neg_hi:[0,1]
	v_pk_add_f32 v[14:15], v[96:97], v[196:197] op_sel_hi:[1,0] neg_lo:[0,1] neg_hi:[0,1]
	v_pk_add_f32 v[66:67], v[82:83], v[196:197] op_sel_hi:[1,0] neg_lo:[0,1] neg_hi:[0,1]
	v_pk_add_f32 v[50:51], v[98:99], v[196:197] op_sel_hi:[1,0] neg_lo:[0,1] neg_hi:[0,1]
	v_max_f32_e32 v64, v48, v49
	v_pk_add_f32 v[68:69], v[84:85], v[196:197] op_sel_hi:[1,0] neg_lo:[0,1] neg_hi:[0,1]
	v_pk_add_f32 v[70:71], v[86:87], v[196:197] op_sel_hi:[1,0] neg_lo:[0,1] neg_hi:[0,1]
	v_max3_f32 v65, v66, v67, v15
	v_max3_f32 v64, v64, v14, v50
	v_pk_add_f32 v[52:53], v[100:101], v[196:197] op_sel_hi:[1,0] neg_lo:[0,1] neg_hi:[0,1]
	v_pk_add_f32 v[54:55], v[102:103], v[196:197] op_sel_hi:[1,0] neg_lo:[0,1] neg_hi:[0,1]
	v_max3_f32 v64, v64, v51, v68
	v_max3_f32 v65, v65, v70, v71
	v_pk_add_f32 v[72:73], v[88:89], v[196:197] op_sel_hi:[1,0] neg_lo:[0,1] neg_hi:[0,1]
	v_pk_add_f32 v[74:75], v[90:91], v[196:197] op_sel_hi:[1,0] neg_lo:[0,1] neg_hi:[0,1]
	v_max3_f32 v64, v64, v69, v52
	v_max3_f32 v65, v65, v54, v55
	v_pk_add_f32 v[56:57], v[104:105], v[196:197] op_sel_hi:[1,0] neg_lo:[0,1] neg_hi:[0,1]
	v_pk_add_f32 v[58:59], v[106:107], v[196:197] op_sel_hi:[1,0] neg_lo:[0,1] neg_hi:[0,1]
	v_max3_f32 v64, v64, v53, v72
	v_max3_f32 v65, v65, v74, v75
	v_pk_add_f32 v[76:77], v[92:93], v[196:197] op_sel_hi:[1,0] neg_lo:[0,1] neg_hi:[0,1]
	v_pk_add_f32 v[78:79], v[94:95], v[196:197] op_sel_hi:[1,0] neg_lo:[0,1] neg_hi:[0,1]
	v_max3_f32 v64, v64, v73, v56
	v_max3_f32 v65, v65, v58, v59
	v_pk_add_f32 v[60:61], v[108:109], v[196:197] op_sel_hi:[1,0] neg_lo:[0,1] neg_hi:[0,1]
	v_pk_add_f32 v[62:63], v[110:111], v[196:197] op_sel_hi:[1,0] neg_lo:[0,1] neg_hi:[0,1]
	v_max3_f32 v64, v64, v57, v76
	v_max3_f32 v65, v65, v78, v79
	v_max3_f32 v64, v64, v77, v60
	v_max3_f32 v65, v65, v62, v63
	v_max3_f32 v64, v64, v61, v65
	v_cmp_lt_f32_e32 vcc, s85, v64
	s_cmp_lg_u64 vcc, 0
	v_add_f32_e32 v0, v220, v0
	s_cselect_b64 s[54:55], -1, 0
	s_cbranch_vccnz .LBB0_1431

.LBB0_1426:
	ds_read_b128 v[222:225], v184 offset:256
	ds_read_b128 v[226:229], v184 offset:384
	ds_read_b128 v[230:233], v184 offset:288
	ds_read_b128 v[242:245], v184 offset:416
	ds_read_b128 v[246:249], v184 offset:320
	ds_read_b128 v[250:253], v184 offset:448
	s_add_i32 s54, s62, 0x2000
	s_cmpk_lg_i32 s62, 0x4000
	s_cselect_b32 s95, s54, 0
	v_add_u32_e32 v4, s97, v219
	ds_read_b64_tr_b16 v[160:161], v4 offset:24576
	ds_read_b64_tr_b16 v[162:163], v4 offset:25088
	v_add_f32_e32 v2, v64, v65
	v_add_f32_e32 v2, v66, v2
	v_add_f32_e32 v2, v67, v2
	v_add_f32_e32 v2, v68, v2
	v_add_f32_e32 v2, v69, v2
	v_cvt_pk_bf16_f32 v132, v64, v65
	v_cvt_pk_bf16_f32 v133, v66, v67
	s_waitcnt lgkmcnt(9)
	v_mfma_f32_32x32x16_bf16 v[80:95], v[80:83], v[140:143], 0
	ds_read_b64_tr_b16 v[156:157], v4 offset:28672
	ds_read_b64_tr_b16 v[158:159], v4 offset:29184
	v_add_f32_e32 v2, v70, v2
	v_add_f32_e32 v2, v71, v2
	v_add_f32_e32 v2, v72, v2
	v_add_f32_e32 v2, v73, v2
	v_cvt_pk_bf16_f32 v134, v68, v69
	v_cvt_pk_bf16_f32 v135, v70, v71
	s_waitcnt lgkmcnt(10)
	v_mfma_f32_32x32x16_bf16 v[96:111], v[96:99], v[140:143], 0
	ds_read_b64_tr_b16 v[152:153], v4 offset:25600
	ds_read_b64_tr_b16 v[154:155], v4 offset:26112
	v_add_f32_e32 v2, v74, v2
	v_add_f32_e32 v2, v75, v2
	v_add_f32_e32 v2, v76, v2
	v_add_f32_e32 v2, v77, v2
	v_cvt_pk_bf16_f32 v124, v72, v73
	v_cvt_pk_bf16_f32 v125, v74, v75
	s_waitcnt lgkmcnt(11)
	v_mfma_f32_32x32x16_bf16 v[80:95], v[148:151], v[136:139], v[80:95]
	ds_read_b64_tr_b16 v[148:149], v4 offset:29696
	ds_read_b64_tr_b16 v[150:151], v4 offset:30208
	v_add_f32_e32 v2, v78, v2
	v_add_f32_e32 v2, v79, v2
	v_add_f32_e32 v2, v48, v2
	v_add_f32_e32 v2, v49, v2
	v_cvt_pk_bf16_f32 v126, v76, v77
	v_cvt_pk_bf16_f32 v127, v78, v79
	s_waitcnt lgkmcnt(12)
	v_mfma_f32_32x32x16_bf16 v[96:111], v[144:147], v[136:139], v[96:111]
	ds_read_b64_tr_b16 v[144:145], v4 offset:26624
	ds_read_b64_tr_b16 v[146:147], v4 offset:27136
	v_add_f32_e32 v2, v50, v2
	v_add_f32_e32 v2, v51, v2
	v_add_f32_e32 v2, v52, v2
	v_add_f32_e32 v2, v53, v2
	v_cvt_pk_bf16_f32 v116, v48, v49
	v_cvt_pk_bf16_f32 v117, v50, v51
	s_waitcnt lgkmcnt(13)
	v_mfma_f32_32x32x16_bf16 v[80:95], v[176:179], v[128:131], v[80:95]
	ds_read_b64_tr_b16 v[10:11], v4 offset:30720
	ds_read_b64_tr_b16 v[12:13], v4 offset:31232
	v_add_f32_e32 v2, v54, v2
	v_add_f32_e32 v2, v55, v2
	v_add_f32_e32 v2, v56, v2
	v_add_f32_e32 v2, v57, v2
	v_cvt_pk_bf16_f32 v118, v52, v53
	v_cvt_pk_bf16_f32 v119, v54, v55
	s_waitcnt lgkmcnt(14)
	v_mfma_f32_32x32x16_bf16 v[96:111], v[168:171], v[128:131], v[96:111]
	ds_read_b64_tr_b16 v[6:7], v4 offset:27648
	ds_read_b64_tr_b16 v[8:9], v4 offset:28160
	v_add_f32_e32 v2, v58, v2
	v_add_f32_e32 v2, v59, v2
	v_add_f32_e32 v2, v60, v2
	v_add_f32_e32 v14, v61, v2
	v_cvt_pk_bf16_f32 v112, v56, v57
	v_cvt_pk_bf16_f32 v113, v58, v59
	s_waitcnt lgkmcnt(14)
	v_mfma_f32_32x32x16_bf16 v[80:95], v[172:175], v[120:123], v[80:95]
	ds_read_b64_tr_b16 v[2:3], v4 offset:31744
	ds_read_b64_tr_b16 v[4:5], v4 offset:32256
	v_add_f32_e32 v14, v62, v14
	v_add_f32_e32 v14, v63, v14
	v_add_f32_e32 v64, 0, v14
	v_cvt_pk_bf16_f32 v114, v60, v61
	v_cvt_pk_bf16_f32 v115, v62, v63
	v_mfma_f32_32x32x16_bf16 v[96:111], v[164:167], v[120:123], v[96:111]
	s_add_i32 s54, s62, s66
	s_mov_b32 s55, m0
	s_mov_b32 m0, s54
	s_nop 0
	global_load_lds_dwordx4 v[182:183], off
	s_mov_b32 m0, s55
	s_add_i32 s54, s95, s67
	s_mov_b32 s55, m0
	s_mov_b32 m0, s54
	s_nop 0
	global_load_lds_dwordx4 v[180:181], off
	s_mov_b32 m0, s55
	ds_read_b128 v[48:51], v184 offset:352
	ds_read_b128 v[52:55], v184 offset:480
	s_waitcnt lgkmcnt(2)
	v_pk_add_f32 v[80:81], v[80:81], v[222:223]
	v_pk_add_f32 v[82:83], v[82:83], v[224:225]
	v_pk_add_f32 v[96:97], v[96:97], v[226:227]
	v_pk_add_f32 v[98:99], v[98:99], v[228:229]
	v_pk_add_f32 v[84:85], v[84:85], v[230:231]
	v_pk_add_f32 v[86:87], v[86:87], v[232:233]
	v_pk_add_f32 v[100:101], v[100:101], v[242:243]
	v_pk_add_f32 v[102:103], v[102:103], v[244:245]
	v_pk_add_f32 v[88:89], v[88:89], v[246:247]
	v_pk_add_f32 v[90:91], v[90:91], v[248:249]
	v_pk_add_f32 v[104:105], v[104:105], v[250:251]
	v_pk_add_f32 v[106:107], v[106:107], v[252:253]
	s_waitcnt lgkmcnt(1)
	v_pk_add_f32 v[92:93], v[92:93], v[48:49]
	v_pk_add_f32 v[94:95], v[94:95], v[50:51]
	s_waitcnt lgkmcnt(0)
	v_pk_add_f32 v[108:109], v[108:109], v[52:53]
	v_pk_add_f32 v[110:111], v[110:111], v[54:55]
	s_nop 0
	s_nop 0
	v_pk_add_f32 v[48:49], v[80:81], v[196:197] op_sel_hi:[1,0] neg_lo:[0,1] neg_hi:[0,1]
	v_pk_add_f32 v[14:15], v[96:97], v[196:197] op_sel_hi:[1,0] neg_lo:[0,1] neg_hi:[0,1]
	v_pk_add_f32 v[66:67], v[82:83], v[196:197] op_sel_hi:[1,0] neg_lo:[0,1] neg_hi:[0,1]
	v_pk_add_f32 v[50:51], v[98:99], v[196:197] op_sel_hi:[1,0] neg_lo:[0,1] neg_hi:[0,1]
	v_max_f32_e32 v65, v48, v49
	v_pk_add_f32 v[68:69], v[84:85], v[196:197] op_sel_hi:[1,0] neg_lo:[0,1] neg_hi:[0,1]
	v_pk_add_f32 v[70:71], v[86:87], v[196:197] op_sel_hi:[1,0] neg_lo:[0,1] neg_hi:[0,1]
	v_max3_f32 v80, v66, v67, v15
	v_max3_f32 v65, v65, v14, v50
	v_pk_add_f32 v[52:53], v[100:101], v[196:197] op_sel_hi:[1,0] neg_lo:[0,1] neg_hi:[0,1]
	v_pk_add_f32 v[54:55], v[102:103], v[196:197] op_sel_hi:[1,0] neg_lo:[0,1] neg_hi:[0,1]
	v_max3_f32 v65, v65, v51, v68
	v_max3_f32 v80, v80, v70, v71
	v_pk_add_f32 v[72:73], v[88:89], v[196:197] op_sel_hi:[1,0] neg_lo:[0,1] neg_hi:[0,1]
	v_pk_add_f32 v[74:75], v[90:91], v[196:197] op_sel_hi:[1,0] neg_lo:[0,1] neg_hi:[0,1]
	v_max3_f32 v65, v65, v69, v52
	v_max3_f32 v80, v80, v54, v55
	v_pk_add_f32 v[56:57], v[104:105], v[196:197] op_sel_hi:[1,0] neg_lo:[0,1] neg_hi:[0,1]
	v_pk_add_f32 v[58:59], v[106:107], v[196:197] op_sel_hi:[1,0] neg_lo:[0,1] neg_hi:[0,1]
	v_max3_f32 v65, v65, v53, v72
	v_max3_f32 v80, v80, v74, v75
	v_pk_add_f32 v[76:77], v[92:93], v[196:197] op_sel_hi:[1,0] neg_lo:[0,1] neg_hi:[0,1]
	v_pk_add_f32 v[78:79], v[94:95], v[196:197] op_sel_hi:[1,0] neg_lo:[0,1] neg_hi:[0,1]
	v_max3_f32 v65, v65, v73, v56
	v_max3_f32 v80, v80, v58, v59
	v_pk_add_f32 v[60:61], v[108:109], v[196:197] op_sel_hi:[1,0] neg_lo:[0,1] neg_hi:[0,1]
	v_pk_add_f32 v[62:63], v[110:111], v[196:197] op_sel_hi:[1,0] neg_lo:[0,1] neg_hi:[0,1]
	v_max3_f32 v65, v65, v57, v76
	v_max3_f32 v80, v80, v78, v79
	v_max3_f32 v65, v65, v77, v60
	v_max3_f32 v80, v80, v62, v63
	v_add_f32_e32 v220, v0, v64
	v_max3_f32 v0, v65, v61, v80
	v_cmp_lt_f32_e32 vcc, s85, v0
	s_cmp_lg_u64 vcc, 0
	s_cselect_b64 s[54:55], -1, 0
	s_cbranch_vccnz .LBB0_1434

.LBB0_1431:
	v_mov_b32_e32 v65, v64
	s_nop 1
	v_permlane32_swap_b32_e32 v64, v65
	v_max_f32_e32 v65, v65, v65
	v_max_f32_e32 v64, v64, v64
	v_max_f32_e32 v64, v64, v65
	v_max_f32_e32 v64, v64, v64
	v_max_f32_e32 v65, 0, v64
	v_exp_f32_e64 v64, -v65
	s_and_saveexec_b64 s[58:59], s[8:9]
	ds_write_b32 v215, v64 offset:49152
	s_or_b64 exec, exec, s[58:59]
	v_sub_f32_e32 v48, v48, v65
	v_sub_f32_e32 v49, v49, v65
	v_sub_f32_e32 v66, v66, v65
	v_sub_f32_e32 v67, v67, v65
	v_sub_f32_e32 v68, v68, v65
	v_sub_f32_e32 v69, v69, v65
	v_sub_f32_e32 v70, v70, v65
	v_sub_f32_e32 v71, v71, v65
	v_sub_f32_e32 v72, v72, v65
	v_sub_f32_e32 v73, v73, v65
	v_sub_f32_e32 v74, v74, v65
	v_sub_f32_e32 v75, v75, v65
	v_sub_f32_e32 v76, v76, v65
	v_sub_f32_e32 v77, v77, v65
	v_sub_f32_e32 v78, v78, v65
	v_sub_f32_e32 v79, v79, v65
	v_sub_f32_e32 v14, v14, v65
	v_sub_f32_e32 v15, v15, v65
	v_sub_f32_e32 v50, v50, v65
	v_sub_f32_e32 v51, v51, v65
	v_sub_f32_e32 v52, v52, v65
	v_sub_f32_e32 v53, v53, v65
	v_sub_f32_e32 v54, v54, v65
	v_sub_f32_e32 v55, v55, v65
	v_sub_f32_e32 v56, v56, v65
	v_sub_f32_e32 v57, v57, v65
	v_sub_f32_e32 v58, v58, v65
	v_sub_f32_e32 v59, v59, v65
	v_sub_f32_e32 v60, v60, v65
	v_sub_f32_e32 v61, v61, v65
	v_sub_f32_e32 v62, v62, v65
	v_sub_f32_e32 v63, v63, v65
	v_add_f32_e32 v196, v196, v65
	v_mul_f32_e32 v0, v0, v64
	s_branch .LBB0_1424
.LBB0_1434:
	v_mov_b32_e32 v64, v0
	s_nop 1
	v_permlane32_swap_b32_e32 v0, v64
	v_max_f32_e32 v64, v64, v64
	v_max_f32_e32 v0, v0, v0
	v_max_f32_e32 v0, v0, v64
	v_max_f32_e32 v0, v0, v0
	v_max_f32_e32 v64, 0, v0
	v_exp_f32_e64 v0, -v64
	s_and_saveexec_b64 s[58:59], s[8:9]
	ds_write_b32 v215, v0 offset:49152
	s_or_b64 exec, exec, s[58:59]
	v_sub_f32_e32 v48, v48, v64
	v_sub_f32_e32 v49, v49, v64
	v_sub_f32_e32 v66, v66, v64
	v_sub_f32_e32 v67, v67, v64
	v_sub_f32_e32 v68, v68, v64
	v_sub_f32_e32 v69, v69, v64
	v_sub_f32_e32 v70, v70, v64
	v_sub_f32_e32 v71, v71, v64
	v_sub_f32_e32 v72, v72, v64
	v_sub_f32_e32 v73, v73, v64
	v_sub_f32_e32 v74, v74, v64
	v_sub_f32_e32 v75, v75, v64
	v_sub_f32_e32 v76, v76, v64
	v_sub_f32_e32 v77, v77, v64
	v_sub_f32_e32 v78, v78, v64
	v_sub_f32_e32 v79, v79, v64
	v_sub_f32_e32 v14, v14, v64
	v_sub_f32_e32 v15, v15, v64
	v_sub_f32_e32 v50, v50, v64
	v_sub_f32_e32 v51, v51, v64
	v_sub_f32_e32 v52, v52, v64
	v_sub_f32_e32 v53, v53, v64
	v_sub_f32_e32 v54, v54, v64
	v_sub_f32_e32 v55, v55, v64
	v_sub_f32_e32 v56, v56, v64
	v_sub_f32_e32 v57, v57, v64
	v_sub_f32_e32 v58, v58, v64
	v_sub_f32_e32 v59, v59, v64
	v_sub_f32_e32 v60, v60, v64
	v_sub_f32_e32 v61, v61, v64
	v_sub_f32_e32 v62, v62, v64
	v_sub_f32_e32 v63, v63, v64
	v_add_f32_e32 v196, v196, v64
	v_mul_f32_e32 v220, v220, v0
	s_branch .LBB0_1427

.LBB0_1439:
	v_add_u32_e32 v0, s96, v219
	ds_read_b64_tr_b16 v[176:177], v0 offset:24576
	ds_read_b64_tr_b16 v[178:179], v0 offset:25088
	v_add_f32_e32 v2, v64, v65
	v_add_f32_e32 v2, v66, v2
	v_add_f32_e32 v2, v67, v2
	v_add_f32_e32 v2, v68, v2
	v_add_f32_e32 v2, v69, v2
	v_cvt_pk_bf16_f32 v132, v64, v65
	v_cvt_pk_bf16_f32 v133, v66, v67
	s_waitcnt lgkmcnt(3)
	v_mfma_f32_32x32x16_bf16 v[80:95], v[172:175], v[140:143], 0
	ds_read_b64_tr_b16 v[172:173], v0 offset:28672
	ds_read_b64_tr_b16 v[174:175], v0 offset:29184
	v_add_f32_e32 v2, v70, v2
	v_add_f32_e32 v2, v71, v2
	v_add_f32_e32 v2, v72, v2
	v_add_f32_e32 v2, v73, v2
	v_cvt_pk_bf16_f32 v134, v68, v69
	v_cvt_pk_bf16_f32 v135, v70, v71
	s_waitcnt lgkmcnt(4)
	v_mfma_f32_32x32x16_bf16 v[96:111], v[168:171], v[140:143], 0
	ds_read_b64_tr_b16 v[168:169], v0 offset:25600
	ds_read_b64_tr_b16 v[170:171], v0 offset:26112
	v_add_f32_e32 v2, v74, v2
	v_add_f32_e32 v2, v75, v2
	v_add_f32_e32 v2, v76, v2
	v_add_f32_e32 v2, v77, v2
	v_cvt_pk_bf16_f32 v124, v72, v73
	v_cvt_pk_bf16_f32 v125, v74, v75
	v_mfma_f32_32x32x16_bf16 v[80:95], v[164:167], v[136:139], v[80:95]
	ds_read_b64_tr_b16 v[140:141], v0 offset:29696
	ds_read_b64_tr_b16 v[142:143], v0 offset:30208
	v_add_f32_e32 v2, v78, v2
	v_add_f32_e32 v2, v79, v2
	v_add_f32_e32 v2, v48, v2
	v_add_f32_e32 v2, v49, v2
	v_cvt_pk_bf16_f32 v126, v76, v77
	v_cvt_pk_bf16_f32 v127, v78, v79
	v_mfma_f32_32x32x16_bf16 v[96:111], v[160:163], v[136:139], v[96:111]
	ds_read_b64_tr_b16 v[136:137], v0 offset:26624
	ds_read_b64_tr_b16 v[138:139], v0 offset:27136
	v_add_f32_e32 v2, v50, v2
	v_add_f32_e32 v2, v51, v2
	v_add_f32_e32 v2, v52, v2
	v_add_f32_e32 v2, v53, v2
	v_cvt_pk_bf16_f32 v116, v48, v49
	v_cvt_pk_bf16_f32 v117, v50, v51
	v_mfma_f32_32x32x16_bf16 v[80:95], v[156:159], v[128:131], v[80:95]
	ds_read_b64_tr_b16 v[10:11], v0 offset:30720
	ds_read_b64_tr_b16 v[12:13], v0 offset:31232
	v_add_f32_e32 v2, v54, v2
	v_add_f32_e32 v2, v55, v2
	v_add_f32_e32 v2, v56, v2
	v_add_f32_e32 v2, v57, v2
	v_cvt_pk_bf16_f32 v118, v52, v53
	v_cvt_pk_bf16_f32 v119, v54, v55
	v_mfma_f32_32x32x16_bf16 v[96:111], v[148:151], v[128:131], v[96:111]
	ds_read_b64_tr_b16 v[6:7], v0 offset:27648
	ds_read_b64_tr_b16 v[8:9], v0 offset:28160
	v_add_f32_e32 v2, v58, v2
	v_add_f32_e32 v2, v59, v2
	v_add_f32_e32 v2, v60, v2
	v_add_f32_e32 v14, v61, v2
	v_cvt_pk_bf16_f32 v112, v56, v57
	v_cvt_pk_bf16_f32 v113, v58, v59
	v_mfma_f32_32x32x16_bf16 v[80:95], v[152:155], v[120:123], v[80:95]
	ds_read_b64_tr_b16 v[2:3], v0 offset:31744
	ds_read_b64_tr_b16 v[4:5], v0 offset:32256
	v_add_f32_e32 v0, v62, v14
	v_add_f32_e32 v0, v63, v0
	v_add_f32_e32 v0, 0, v0
	v_cvt_pk_bf16_f32 v114, v60, v61
	v_cvt_pk_bf16_f32 v115, v62, v63
	v_mfma_f32_32x32x16_bf16 v[96:111], v[144:147], v[120:123], v[96:111]
	s_lshl_b32 s8, s23, 8
	s_add_i32 s21, s21, s8
	v_lshl_add_u32 v14, v216, 2, s21
	v_add_u32_e32 v14, 0xffffff00, v14
	ds_read_b128 v[48:51], v14
	ds_read_b128 v[52:55], v14 offset:128
	s_waitcnt lgkmcnt(1)
	v_pk_add_f32 v[80:81], v[80:81], v[48:49]
	v_pk_add_f32 v[82:83], v[82:83], v[50:51]
	s_waitcnt lgkmcnt(0)
	s_nop 1
	v_pk_add_f32 v[96:97], v[96:97], v[52:53]
	v_pk_add_f32 v[98:99], v[98:99], v[54:55]
	s_nop 0
	ds_read_b128 v[48:51], v14 offset:32
	ds_read_b128 v[52:55], v14 offset:160
	s_waitcnt lgkmcnt(1)
	v_pk_add_f32 v[84:85], v[84:85], v[48:49]
	v_pk_add_f32 v[86:87], v[86:87], v[50:51]
	s_waitcnt lgkmcnt(0)
	v_pk_add_f32 v[100:101], v[100:101], v[52:53]
	v_pk_add_f32 v[102:103], v[102:103], v[54:55]
	s_nop 0
	ds_read_b128 v[48:51], v14 offset:64
	ds_read_b128 v[52:55], v14 offset:192
	s_waitcnt lgkmcnt(1)
	v_pk_add_f32 v[88:89], v[88:89], v[48:49]
	v_pk_add_f32 v[90:91], v[90:91], v[50:51]
	s_waitcnt lgkmcnt(0)
	v_pk_add_f32 v[104:105], v[104:105], v[52:53]
	v_pk_add_f32 v[106:107], v[106:107], v[54:55]
	s_nop 0
	ds_read_b128 v[48:51], v14 offset:96
	ds_read_b128 v[52:55], v14 offset:224
	s_waitcnt lgkmcnt(1)
	v_pk_add_f32 v[92:93], v[92:93], v[48:49]
	v_pk_add_f32 v[94:95], v[94:95], v[50:51]
	s_waitcnt lgkmcnt(0)
; __device__ __forceinline__ void cmask(f32x16&p0,f32x16&p1,int jb,int qrel,int hi){
;   const float NEG=-INFINITY; int kb=64*jb+4*hi;
;   #pragma unroll
;   for(int r=0;r<16;++r){int kv=kb+(r&3)+8*(r>>2); if(kv>qrel)p0[r]=NEG; if(kv+32>qrel)p1[r]=NEG;}
; }
	v_pk_add_f32 v[108:109], v[108:109], v[52:53]
	v_pk_add_f32 v[110:111], v[110:111], v[54:55]
	s_nop 0
	v_or_b32_e32 v14, 0xe0, v216
	v_or_b32_e32 v15, 0xc0, v216
	v_cmp_le_u32_e32 vcc, v14, v217
	v_or_b32_e32 v50, 0xc2, v216
	v_or_b32_e32 v51, 0xe2, v216
	v_cndmask_b32_e32 v14, v205, v96, vcc
	v_cmp_lt_u32_e32 vcc, v15, v217
	v_or_b32_e32 v53, 0xe3, v216
	v_or_b32_e32 v54, 0xc8, v216
	v_cndmask_b32_e32 v49, v205, v81, vcc
	v_cmp_le_u32_e32 vcc, v15, v217
	v_or_b32_e32 v15, 0xe1, v216
	v_or_b32_e32 v55, 0xe8, v216
	v_cndmask_b32_e32 v48, v205, v80, vcc
	v_cmp_le_u32_e32 vcc, v15, v217
	v_or_b32_e32 v57, 0xe9, v216
	v_or_b32_e32 v58, 0xca, v216
	v_cndmask_b32_e32 v15, v205, v97, vcc
	v_cmp_le_u32_e32 vcc, v50, v217
	v_or_b32_e32 v59, 0xea, v216
	v_or_b32_e32 v61, 0xeb, v216
	v_cndmask_b32_e32 v50, v205, v82, vcc
	v_cmp_le_u32_e32 vcc, v51, v217
	v_or_b32_e32 v51, 0xc3, v216
	v_or_b32_e32 v62, 0xd0, v216
	v_cndmask_b32_e32 v52, v205, v98, vcc
	v_cmp_le_u32_e32 vcc, v51, v217
	v_or_b32_e32 v63, 0xf0, v216
	v_or_b32_e32 v65, 0xf1, v216
	v_cndmask_b32_e32 v51, v205, v83, vcc
	v_cmp_le_u32_e32 vcc, v53, v217
	v_or_b32_e32 v66, 0xd2, v216
	v_pk_add_f32 v[48:49], v[48:49], v[196:197] op_sel_hi:[1,0] neg_lo:[0,1] neg_hi:[0,1]
	v_cndmask_b32_e32 v53, v205, v99, vcc
	v_cmp_le_u32_e32 vcc, v54, v217
	v_pk_add_f32 v[14:15], v[14:15], v[196:197] op_sel_hi:[1,0] neg_lo:[0,1] neg_hi:[0,1]
	v_add_f32_e32 v0, v220, v0
	v_cndmask_b32_e32 v54, v205, v84, vcc
	v_cmp_le_u32_e32 vcc, v55, v217
	v_or_b32_e32 v55, 0xc9, v216
	s_nop 0
	v_cndmask_b32_e32 v56, v205, v100, vcc
	v_cmp_le_u32_e32 vcc, v55, v217
	s_nop 1
	v_cndmask_b32_e32 v55, v205, v85, vcc
	v_cmp_le_u32_e32 vcc, v57, v217
	v_pk_add_f32 v[68:69], v[54:55], v[196:197] op_sel_hi:[1,0] neg_lo:[0,1] neg_hi:[0,1]
	s_nop 0
	v_cndmask_b32_e32 v57, v205, v101, vcc
	v_cmp_le_u32_e32 vcc, v58, v217
	s_nop 1
	v_cndmask_b32_e32 v58, v205, v86, vcc
	v_cmp_le_u32_e32 vcc, v59, v217
	v_or_b32_e32 v59, 0xcb, v216
	s_nop 0
	v_cndmask_b32_e32 v60, v205, v102, vcc
	v_cmp_le_u32_e32 vcc, v59, v217
	s_nop 1
	v_cndmask_b32_e32 v59, v205, v87, vcc
	v_cmp_le_u32_e32 vcc, v61, v217
	v_pk_add_f32 v[70:71], v[58:59], v[196:197] op_sel_hi:[1,0] neg_lo:[0,1] neg_hi:[0,1]
	s_nop 0
	v_cndmask_b32_e32 v61, v205, v103, vcc
	v_cmp_le_u32_e32 vcc, v62, v217
	v_pk_add_f32 v[54:55], v[60:61], v[196:197] op_sel_hi:[1,0] neg_lo:[0,1] neg_hi:[0,1]
	s_nop 0
	v_cndmask_b32_e32 v62, v205, v88, vcc
	v_cmp_le_u32_e32 vcc, v63, v217
	v_or_b32_e32 v63, 0xd1, v216
	s_nop 0
	v_cndmask_b32_e32 v64, v205, v104, vcc
	v_cmp_le_u32_e32 vcc, v63, v217
	s_nop 1
	v_cndmask_b32_e32 v63, v205, v89, vcc
	v_cmp_le_u32_e32 vcc, v65, v217
	v_pk_add_f32 v[72:73], v[62:63], v[196:197] op_sel_hi:[1,0] neg_lo:[0,1] neg_hi:[0,1]
	s_nop 0
	v_cndmask_b32_e32 v65, v205, v105, vcc
	v_cmp_le_u32_e32 vcc, v66, v217
	v_or_b32_e32 v66, 0xf2, v216
	s_nop 0
	v_cndmask_b32_e32 v74, v205, v90, vcc
	v_cmp_le_u32_e32 vcc, v66, v217
	v_or_b32_e32 v66, 0xd3, v216
	s_nop 0
	v_cndmask_b32_e32 v76, v205, v106, vcc
	v_cmp_le_u32_e32 vcc, v66, v217
	v_or_b32_e32 v66, 0xf3, v216
	s_nop 0
	v_cndmask_b32_e32 v75, v205, v91, vcc
	v_cmp_le_u32_e32 vcc, v66, v217
	v_or_b32_e32 v66, 0xd8, v216
	v_pk_add_f32 v[74:75], v[74:75], v[196:197] op_sel_hi:[1,0] neg_lo:[0,1] neg_hi:[0,1]
	v_cndmask_b32_e32 v77, v205, v107, vcc
	v_cmp_le_u32_e32 vcc, v66, v217
	v_or_b32_e32 v66, 0xf8, v216
	v_pk_add_f32 v[58:59], v[76:77], v[196:197] op_sel_hi:[1,0] neg_lo:[0,1] neg_hi:[0,1]
	v_cndmask_b32_e32 v78, v205, v92, vcc
	v_cmp_le_u32_e32 vcc, v66, v217
	v_or_b32_e32 v66, 0xd9, v216
	s_nop 0
	v_cndmask_b32_e32 v80, v205, v108, vcc
	v_cmp_le_u32_e32 vcc, v66, v217
	v_or_b32_e32 v66, 0xf9, v216
	s_nop 0
	v_cndmask_b32_e32 v79, v205, v93, vcc
	v_cmp_le_u32_e32 vcc, v66, v217
	v_or_b32_e32 v66, 0xda, v216
	v_pk_add_f32 v[76:77], v[78:79], v[196:197] op_sel_hi:[1,0] neg_lo:[0,1] neg_hi:[0,1]
	v_cndmask_b32_e32 v81, v205, v109, vcc
	v_cmp_le_u32_e32 vcc, v66, v217
	v_or_b32_e32 v66, 0xfa, v216
	v_pk_add_f32 v[60:61], v[80:81], v[196:197] op_sel_hi:[1,0] neg_lo:[0,1] neg_hi:[0,1]
	v_cndmask_b32_e32 v82, v205, v94, vcc
	v_cmp_le_u32_e32 vcc, v66, v217
	v_or_b32_e32 v66, 0xdb, v216
	s_nop 0
	v_cndmask_b32_e32 v84, v205, v110, vcc
	v_cmp_le_u32_e32 vcc, v66, v217
	v_or_b32_e32 v66, 0xfb, v216
	s_nop 0
	v_cndmask_b32_e32 v83, v205, v95, vcc
	v_cmp_le_u32_e32 vcc, v66, v217
	v_pk_add_f32 v[66:67], v[50:51], v[196:197] op_sel_hi:[1,0] neg_lo:[0,1] neg_hi:[0,1]
	v_pk_add_f32 v[50:51], v[52:53], v[196:197] op_sel_hi:[1,0] neg_lo:[0,1] neg_hi:[0,1]
	v_pk_add_f32 v[52:53], v[56:57], v[196:197] op_sel_hi:[1,0] neg_lo:[0,1] neg_hi:[0,1]
	v_pk_add_f32 v[56:57], v[64:65], v[196:197] op_sel_hi:[1,0] neg_lo:[0,1] neg_hi:[0,1]
	v_max_f32_e32 v64, v48, v49
	v_max3_f32 v65, v66, v67, v15
	v_max3_f32 v64, v64, v14, v50
	v_max3_f32 v64, v64, v51, v68
	v_max3_f32 v65, v65, v70, v71
	v_max3_f32 v64, v64, v69, v52
	v_max3_f32 v65, v65, v54, v55
	v_max3_f32 v64, v64, v53, v72
	v_max3_f32 v65, v65, v74, v75
	v_cndmask_b32_e32 v85, v205, v111, vcc
	v_pk_add_f32 v[78:79], v[82:83], v[196:197] op_sel_hi:[1,0] neg_lo:[0,1] neg_hi:[0,1]
	v_max3_f32 v64, v64, v73, v56
	v_max3_f32 v65, v65, v58, v59
	v_pk_add_f32 v[62:63], v[84:85], v[196:197] op_sel_hi:[1,0] neg_lo:[0,1] neg_hi:[0,1]
	v_max3_f32 v64, v64, v57, v76
	v_max3_f32 v65, v65, v78, v79
	v_max3_f32 v64, v64, v77, v60
	v_max3_f32 v65, v65, v62, v63
	v_max3_f32 v64, v64, v61, v65
	v_cmp_lt_f32_e32 vcc, s85, v64
	s_cmp_lg_u64 vcc, 0
	s_cselect_b64 s[8:9], -1, 0
	s_cbranch_vccnz .LBB0_1494

.LBB0_1450:
	v_pk_add_f32 v[48:49], v[80:81], v[196:197] op_sel_hi:[1,0] neg_lo:[0,1] neg_hi:[0,1]
	v_add_f32_e32 v220, v220, v14
	v_pk_add_f32 v[14:15], v[96:97], v[196:197] op_sel_hi:[1,0] neg_lo:[0,1] neg_hi:[0,1]
	v_pk_add_f32 v[66:67], v[82:83], v[196:197] op_sel_hi:[1,0] neg_lo:[0,1] neg_hi:[0,1]
	v_pk_add_f32 v[50:51], v[98:99], v[196:197] op_sel_hi:[1,0] neg_lo:[0,1] neg_hi:[0,1]
	v_max_f32_e32 v64, v48, v49
	v_pk_add_f32 v[68:69], v[84:85], v[196:197] op_sel_hi:[1,0] neg_lo:[0,1] neg_hi:[0,1]
	v_pk_add_f32 v[70:71], v[86:87], v[196:197] op_sel_hi:[1,0] neg_lo:[0,1] neg_hi:[0,1]
	v_max3_f32 v65, v66, v67, v15
	v_max3_f32 v64, v64, v14, v50
	v_pk_add_f32 v[52:53], v[100:101], v[196:197] op_sel_hi:[1,0] neg_lo:[0,1] neg_hi:[0,1]
	v_pk_add_f32 v[54:55], v[102:103], v[196:197] op_sel_hi:[1,0] neg_lo:[0,1] neg_hi:[0,1]
	v_max3_f32 v64, v64, v51, v68
	v_max3_f32 v65, v65, v70, v71
	v_pk_add_f32 v[72:73], v[88:89], v[196:197] op_sel_hi:[1,0] neg_lo:[0,1] neg_hi:[0,1]
	v_pk_add_f32 v[74:75], v[90:91], v[196:197] op_sel_hi:[1,0] neg_lo:[0,1] neg_hi:[0,1]
	v_max3_f32 v64, v64, v69, v52
	v_max3_f32 v65, v65, v54, v55
	v_pk_add_f32 v[56:57], v[104:105], v[196:197] op_sel_hi:[1,0] neg_lo:[0,1] neg_hi:[0,1]
	v_pk_add_f32 v[58:59], v[106:107], v[196:197] op_sel_hi:[1,0] neg_lo:[0,1] neg_hi:[0,1]
	v_max3_f32 v64, v64, v53, v72
	v_max3_f32 v65, v65, v74, v75
	v_pk_add_f32 v[76:77], v[92:93], v[196:197] op_sel_hi:[1,0] neg_lo:[0,1] neg_hi:[0,1]
	v_pk_add_f32 v[78:79], v[94:95], v[196:197] op_sel_hi:[1,0] neg_lo:[0,1] neg_hi:[0,1]
	v_max3_f32 v64, v64, v73, v56
	v_max3_f32 v65, v65, v58, v59
	v_pk_add_f32 v[60:61], v[108:109], v[196:197] op_sel_hi:[1,0] neg_lo:[0,1] neg_hi:[0,1]
	v_pk_add_f32 v[62:63], v[110:111], v[196:197] op_sel_hi:[1,0] neg_lo:[0,1] neg_hi:[0,1]
	v_max3_f32 v64, v64, v57, v76
	v_max3_f32 v65, v65, v78, v79
	v_max3_f32 v64, v64, v77, v60
	v_max3_f32 v65, v65, v62, v63
	v_max3_f32 v64, v64, v61, v65
	v_cmp_lt_f32_e32 vcc, s85, v64
	s_cmp_lg_u64 vcc, 0
	s_cselect_b64 s[58:59], -1, 0
	s_cbranch_vccnz .LBB0_1488

.LBB0_1461:
	v_pk_add_f32 v[48:49], v[80:81], v[196:197] op_sel_hi:[1,0] neg_lo:[0,1] neg_hi:[0,1]
	v_add_f32_e32 v220, v220, v14
	v_pk_add_f32 v[14:15], v[96:97], v[196:197] op_sel_hi:[1,0] neg_lo:[0,1] neg_hi:[0,1]
	v_pk_add_f32 v[66:67], v[82:83], v[196:197] op_sel_hi:[1,0] neg_lo:[0,1] neg_hi:[0,1]
	v_pk_add_f32 v[50:51], v[98:99], v[196:197] op_sel_hi:[1,0] neg_lo:[0,1] neg_hi:[0,1]
	v_max_f32_e32 v64, v48, v49
	v_pk_add_f32 v[68:69], v[84:85], v[196:197] op_sel_hi:[1,0] neg_lo:[0,1] neg_hi:[0,1]
	v_pk_add_f32 v[70:71], v[86:87], v[196:197] op_sel_hi:[1,0] neg_lo:[0,1] neg_hi:[0,1]
	v_max3_f32 v65, v66, v67, v15
	v_max3_f32 v64, v64, v14, v50
	v_pk_add_f32 v[52:53], v[100:101], v[196:197] op_sel_hi:[1,0] neg_lo:[0,1] neg_hi:[0,1]
	v_pk_add_f32 v[54:55], v[102:103], v[196:197] op_sel_hi:[1,0] neg_lo:[0,1] neg_hi:[0,1]
	v_max3_f32 v64, v64, v51, v68
	v_max3_f32 v65, v65, v70, v71
	v_pk_add_f32 v[72:73], v[88:89], v[196:197] op_sel_hi:[1,0] neg_lo:[0,1] neg_hi:[0,1]
	v_pk_add_f32 v[74:75], v[90:91], v[196:197] op_sel_hi:[1,0] neg_lo:[0,1] neg_hi:[0,1]
	v_max3_f32 v64, v64, v69, v52
	v_max3_f32 v65, v65, v54, v55
	v_pk_add_f32 v[56:57], v[104:105], v[196:197] op_sel_hi:[1,0] neg_lo:[0,1] neg_hi:[0,1]
	v_pk_add_f32 v[58:59], v[106:107], v[196:197] op_sel_hi:[1,0] neg_lo:[0,1] neg_hi:[0,1]
	v_max3_f32 v64, v64, v53, v72
	v_max3_f32 v65, v65, v74, v75
	v_pk_add_f32 v[76:77], v[92:93], v[196:197] op_sel_hi:[1,0] neg_lo:[0,1] neg_hi:[0,1]
	v_pk_add_f32 v[78:79], v[94:95], v[196:197] op_sel_hi:[1,0] neg_lo:[0,1] neg_hi:[0,1]
	v_max3_f32 v64, v64, v73, v56
	v_max3_f32 v65, v65, v58, v59
	v_pk_add_f32 v[60:61], v[108:109], v[196:197] op_sel_hi:[1,0] neg_lo:[0,1] neg_hi:[0,1]
	v_pk_add_f32 v[62:63], v[110:111], v[196:197] op_sel_hi:[1,0] neg_lo:[0,1] neg_hi:[0,1]
	v_max3_f32 v64, v64, v57, v76
	v_max3_f32 v65, v65, v78, v79
	v_max3_f32 v64, v64, v77, v60
	v_max3_f32 v65, v65, v62, v63
	v_max3_f32 v64, v64, v61, v65
	v_cmp_lt_f32_e32 vcc, s85, v64
	s_cmp_lg_u64 vcc, 0
	s_cselect_b64 s[62:63], -1, 0
	s_cbranch_vccnz .LBB0_1491

.LBB0_1488:
	v_mov_b32_e32 v65, v64
	s_nop 1
	v_permlane32_swap_b32_e32 v64, v65
	v_max_f32_e32 v65, v65, v65
	v_max_f32_e32 v64, v64, v64
	v_max_f32_e32 v64, v64, v65
	v_max_f32_e32 v64, v64, v64
	v_max_f32_e32 v65, 0, v64
	v_exp_f32_e64 v64, -v65
	s_and_saveexec_b64 s[60:61], s[8:9]
	ds_write_b32 v215, v64 offset:49152
	s_or_b64 exec, exec, s[60:61]
	v_sub_f32_e32 v48, v48, v65
	v_sub_f32_e32 v49, v49, v65
	v_sub_f32_e32 v66, v66, v65
	v_sub_f32_e32 v67, v67, v65
	v_sub_f32_e32 v68, v68, v65
	v_sub_f32_e32 v69, v69, v65
	v_sub_f32_e32 v70, v70, v65
	v_sub_f32_e32 v71, v71, v65
	v_sub_f32_e32 v72, v72, v65
	v_sub_f32_e32 v73, v73, v65
	v_sub_f32_e32 v74, v74, v65
	v_sub_f32_e32 v75, v75, v65
	v_sub_f32_e32 v76, v76, v65
	v_sub_f32_e32 v77, v77, v65
	v_sub_f32_e32 v78, v78, v65
	v_sub_f32_e32 v79, v79, v65
	v_sub_f32_e32 v14, v14, v65
	v_sub_f32_e32 v15, v15, v65
	v_sub_f32_e32 v50, v50, v65
	v_sub_f32_e32 v51, v51, v65
	v_sub_f32_e32 v52, v52, v65
	v_sub_f32_e32 v53, v53, v65
	v_sub_f32_e32 v54, v54, v65
	v_sub_f32_e32 v55, v55, v65
	v_sub_f32_e32 v56, v56, v65
	v_sub_f32_e32 v57, v57, v65
	v_sub_f32_e32 v58, v58, v65
	v_sub_f32_e32 v59, v59, v65
	v_sub_f32_e32 v60, v60, v65
	v_sub_f32_e32 v61, v61, v65
	v_sub_f32_e32 v62, v62, v65
	v_sub_f32_e32 v63, v63, v65
	v_add_f32_e32 v196, v196, v65
	v_mul_f32_e32 v220, v220, v64
	s_branch .LBB0_1451
.LBB0_1491:
	v_mov_b32_e32 v65, v64
	s_nop 1
	v_permlane32_swap_b32_e32 v64, v65
	v_max_f32_e32 v65, v65, v65
	v_max_f32_e32 v64, v64, v64
	v_max_f32_e32 v64, v64, v65
	v_max_f32_e32 v64, v64, v64
	v_max_f32_e32 v65, 0, v64
	v_exp_f32_e64 v64, -v65
	s_and_saveexec_b64 s[10:11], s[8:9]
	ds_write_b32 v215, v64 offset:49152
	s_or_b64 exec, exec, s[10:11]
	v_sub_f32_e32 v48, v48, v65
	v_sub_f32_e32 v49, v49, v65
	v_sub_f32_e32 v66, v66, v65
	v_sub_f32_e32 v67, v67, v65
	v_sub_f32_e32 v68, v68, v65
	v_sub_f32_e32 v69, v69, v65
	v_sub_f32_e32 v70, v70, v65
	v_sub_f32_e32 v71, v71, v65
	v_sub_f32_e32 v72, v72, v65
	v_sub_f32_e32 v73, v73, v65
	v_sub_f32_e32 v74, v74, v65
	v_sub_f32_e32 v75, v75, v65
	v_sub_f32_e32 v76, v76, v65
	v_sub_f32_e32 v77, v77, v65
	v_sub_f32_e32 v78, v78, v65
	v_sub_f32_e32 v79, v79, v65
	v_sub_f32_e32 v14, v14, v65
	v_sub_f32_e32 v15, v15, v65
	v_sub_f32_e32 v50, v50, v65
	v_sub_f32_e32 v51, v51, v65
	v_sub_f32_e32 v52, v52, v65
	v_sub_f32_e32 v53, v53, v65
	v_sub_f32_e32 v54, v54, v65
	v_sub_f32_e32 v55, v55, v65
	v_sub_f32_e32 v56, v56, v65
	v_sub_f32_e32 v57, v57, v65
	v_sub_f32_e32 v58, v58, v65
	v_sub_f32_e32 v59, v59, v65
	v_sub_f32_e32 v60, v60, v65
	v_sub_f32_e32 v61, v61, v65
	v_sub_f32_e32 v62, v62, v65
	v_sub_f32_e32 v63, v63, v65
	v_add_f32_e32 v196, v196, v65
	v_mul_f32_e32 v220, v220, v64
	s_branch .LBB0_1462
.LBB0_1494:
	v_mov_b32_e32 v65, v64
	s_nop 1
	v_permlane32_swap_b32_e32 v64, v65
	v_max_f32_e32 v65, v65, v65
	v_max_f32_e32 v64, v64, v64
	v_max_f32_e32 v64, v64, v65
	v_max_f32_e32 v64, v64, v64
	v_max_f32_e32 v65, 0, v64
	v_exp_f32_e64 v64, -v65
	v_cmp_gt_u32_e32 vcc, 32, v207
	s_and_saveexec_b64 s[10:11], vcc
	ds_write_b32 v215, v64 offset:49152
	s_or_b64 exec, exec, s[10:11]
	v_sub_f32_e32 v48, v48, v65
	v_sub_f32_e32 v49, v49, v65
	v_sub_f32_e32 v66, v66, v65
	v_sub_f32_e32 v67, v67, v65
	v_sub_f32_e32 v68, v68, v65
	v_sub_f32_e32 v69, v69, v65
	v_sub_f32_e32 v70, v70, v65
	v_sub_f32_e32 v71, v71, v65
	v_sub_f32_e32 v72, v72, v65
	v_sub_f32_e32 v73, v73, v65
	v_sub_f32_e32 v74, v74, v65
	v_sub_f32_e32 v75, v75, v65
	v_sub_f32_e32 v76, v76, v65
	v_sub_f32_e32 v77, v77, v65
	v_sub_f32_e32 v78, v78, v65
	v_sub_f32_e32 v79, v79, v65
	v_sub_f32_e32 v14, v14, v65
	v_sub_f32_e32 v15, v15, v65
	v_sub_f32_e32 v50, v50, v65
	v_sub_f32_e32 v51, v51, v65
	v_sub_f32_e32 v52, v52, v65
	v_sub_f32_e32 v53, v53, v65
	v_sub_f32_e32 v54, v54, v65
	v_sub_f32_e32 v55, v55, v65
	v_sub_f32_e32 v56, v56, v65
	v_sub_f32_e32 v57, v57, v65
	v_sub_f32_e32 v58, v58, v65
	v_sub_f32_e32 v59, v59, v65
	v_sub_f32_e32 v60, v60, v65
	v_sub_f32_e32 v61, v61, v65
	v_sub_f32_e32 v62, v62, v65
	v_sub_f32_e32 v63, v63, v65
	v_mul_f32_e32 v0, v0, v64
	s_branch .LBB0_1440
